# sample-sequence scan: recurrent state moved with 16-byte loads/stores plus an in-register 4x4 quad transpose (DPP) instead of 32 dword accesses per lane
# baseline (speedup 1.0000x reference)
; #define LAS __attribute__((address_space(3)))
; __device__ __forceinline__ void hg_seq(const Frame& F, unsigned char* ws, const float* s0, float* sout, float* Og, int seq, bool sample, int vs_base, int nvs) {
;     LAS unsigned char* ring = F.lds;
;     const int tid = F.tid, lane = F.lane, vs = vs_base + F.wave, r = lane & 15, q = lane >> 4;
;     const bool active = F.wave < nvs, vload = (unsigned)((tid >> 6) - vs_base) < (unsigned)nvs;
;     int nch, nvalid, t0, h; const unsigned char *qf, *vf, *lf; int qp, lp; size_t qstep, lstep;
;     if (!sample) { const int b = seq >> 2; h = seq & 3; t0 = b * 2048; nch = 64; nvalid = 32; const size_t e0 = (size_t)t0 * DA + h * 128;
;         qf = ws + WS_Q + e0 * 2; vf = ws + WS_V + e0 * 2; lf = ws + WS_LOGF + e0 * 4; qp = 1024; lp = 2048; qstep = 32 * 1024; lstep = 32 * 2048; }
;     else { const int b = seq >> 2; h = seq & 3; t0 = TP + b * 8; nch = 1; nvalid = 8; const unsigned char* base = (const unsigned char*)sout + (size_t)seq * 65536;
;         qf = base; vf = base + 8192; lf = base + 16384; qp = 256; lp = 512; qstep = 0; lstep = 0; }
;     const size_t offq = (size_t)(tid >> 4) * qp + (tid & 15) * 16, offl0 = (size_t)(tid >> 5) * lp + (tid & 31) * 16, offl1 = (size_t)(16 + (tid >> 5)) * lp + (tid & 31) * 16, offl1c = tid < 160 ? offl1 : offl0;
;     {
;     f32x4 S[8];
;     if (sample && active) {
; #pragma unroll
;         for (int kb = 0; kb < 8; ++kb)
; #pragma unroll
;             for (int i = 0; i < 4; ++i) S[kb][i] = s0[((size_t)seq * 128 + 16 * kb + 4 * q + i) * 128 + 16 * vs + r];
;     } else {
.LBB0_1113:
	s_and_b64 vcc, exec, s[6:7]
	s_cbranch_vccz .LBB0_1246
	s_cmpk_gt_i32 s2, 0x7f
	v_and_b32_e32 v162, 15, v189
	s_waitcnt vmcnt(3)
	v_ashrrev_i32_e32 v52, 4, v188
	v_lshlrev_b32_e32 v101, 4, v188
	v_ashrrev_i32_e32 v50, 5, v188
	v_lshrrev_b32_e32 v100, 2, v189
	v_lshlrev_b32_e32 v98, 4, v189
	v_and_b32_e32 v99, 48, v189
	s_cbranch_scc1 .LBB0_1139
	s_mov_b64 exec, -1
	s_waitcnt lgkmcnt(0)
	s_lshl_b32 s3, s2, 16
	s_add_u32 s8, s16, s3
	s_addc_u32 s9, s17, 0
	s_add_u32 s10, s20, 0x4608000
	s_addc_u32 s11, s21, 0
	s_add_u32 s10, s10, s3
	s_addc_u32 s11, s11, 0
	s_lshr_b32 s6, s2, 2
	s_lshl_b32 s6, s6, 14
	s_and_b32 s7, s2, 3
	s_lshl_b32 s7, s7, 9
	s_add_i32 s6, s6, s7
	s_add_u32 s12, s22, 0x4080000
	s_addc_u32 s13, s23, 0
	s_add_u32 s12, s12, s6
	s_addc_u32 s13, s13, 0
	s_mov_b32 s34, 0x800000
	s_mov_b32 s35, 0
	v_lshlrev_b32_e32 v142, 4, v189
	s_lshl_b32 s3, s50, 10
	v_add_u32_e32 v143, s3, v142
	v_lshrrev_b32_e32 v1, 4, v189
	v_lshlrev_b32_e32 v144, 4, v1
	s_lshl_b32 s3, s50, 4
	v_and_b32_e32 v2, 15, v189
	v_add_u32_e32 v2, s3, v2
	v_lshlrev_b32_e32 v2, 2, v2
	v_lshl_add_u32 v208, v1, 13, v2
	v_add_u32_e32 v209, 0x1000, v208
	v_and_b32_e32 v3, 3, v189
	v_lshlrev_b32_e32 v3, 9, v3
	v_lshl_add_u32 v3, v1, 11, v3
	v_bfe_u32 v200, v189, 2, 2
	v_lshl_add_u32 v3, v200, 4, v3
	s_lshl_b32 s3, s50, 6
	v_add_u32_e32 v200, s3, v3
	v_add_u32_e32 v201, 0x2000, v200
	v_add_u32_e32 v202, 0x4000, v200
	v_add_u32_e32 v203, 0x6000, v200
	v_add_u32_e32 v204, 0x8000, v200
	v_add_u32_e32 v205, 0xa000, v200
	v_add_u32_e32 v206, 0xc000, v200
	v_add_u32_e32 v207, 0xe000, v200
	s_mov_b32 s42, 0x55555555
	s_mov_b32 s43, 0x55555555
	s_mov_b32 s44, 0x33333333
	s_mov_b32 s45, 0x33333333
	v_mov_b32_e32 v3, 0
	v_mov_b32_e32 v2, v143
	v_lshl_add_u64 v[210:211], s[10:11], 0, v[2:3]
	s_add_u32 s6, s10, 0x2000
	s_addc_u32 s7, s11, 0
	v_lshl_add_u64 v[212:213], s[6:7], 0, v[2:3]
	s_add_u32 s6, s10, 0x4000
	s_addc_u32 s7, s11, 0
	v_lshl_add_u64 v[214:215], s[6:7], 0, v[2:3]
	s_mov_b32 s36, 0
	s_lshl_b32 s37, s50, 10
	s_cmp_lt_u32 s50, 3
	s_cbranch_scc0 .Lsmp_p4_done
	s_movk_i32 s36, 0x6000
	s_add_i32 s37, s37, 0x6000
.Lsmp_p4_done:
	s_add_u32 s6, s10, s36
	s_addc_u32 s7, s11, 0
	v_lshl_add_u64 v[140:141], s[6:7], 0, v[2:3]
	s_lshl_b32 s38, s50, 10
	s_add_i32 s39, s38, 0x4000
	s_add_i32 s40, s38, 0x2000
	s_mov_b32 m0, s38
	s_nop 0
	global_load_lds_dwordx4 v[210:211], off
	s_mov_b32 m0, s39
	s_nop 0
	global_load_lds_dwordx4 v[212:213], off
	s_mov_b32 m0, s40
	s_nop 0
	global_load_lds_dwordx4 v[214:215], off
	s_mov_b32 m0, s37
	s_nop 0
	global_load_lds_dwordx4 v[140:141], off
	v_lshl_add_u64 v[210:211], v[210:211], 0, s[34:35]
	v_lshl_add_u64 v[212:213], v[212:213], 0, s[34:35]
	v_lshl_add_u64 v[214:215], v[214:215], 0, s[34:35]
	v_lshl_add_u64 v[140:141], v[140:141], 0, s[34:35]
	s_add_i32 m0, s38, 0x6c00
	s_nop 0
	global_load_lds_dwordx4 v[210:211], off
	s_add_i32 m0, s39, 0x6c00
	s_nop 0
	global_load_lds_dwordx4 v[212:213], off
	s_add_i32 m0, s40, 0x6c00
	s_nop 0
	global_load_lds_dwordx4 v[214:215], off
	s_add_i32 m0, s37, 0x6c00
	s_nop 0
	global_load_lds_dwordx4 v[140:141], off
	v_lshl_add_u64 v[210:211], v[210:211], 0, s[34:35]
	v_lshl_add_u64 v[212:213], v[212:213], 0, s[34:35]
	v_lshl_add_u64 v[214:215], v[214:215], 0, s[34:35]
	v_lshl_add_u64 v[140:141], v[140:141], 0, s[34:35]
	s_add_i32 m0, s38, 0xd800
	s_nop 0
	global_load_lds_dwordx4 v[210:211], off
	s_add_i32 m0, s39, 0xd800
	s_nop 0
	global_load_lds_dwordx4 v[212:213], off
	s_add_i32 m0, s40, 0xd800
	s_nop 0
	global_load_lds_dwordx4 v[214:215], off
	s_add_i32 m0, s37, 0xd800
	s_nop 0
	global_load_lds_dwordx4 v[140:141], off
	v_lshl_add_u64 v[210:211], v[210:211], 0, s[34:35]
	v_lshl_add_u64 v[212:213], v[212:213], 0, s[34:35]
	v_lshl_add_u64 v[214:215], v[214:215], 0, s[34:35]
	v_lshl_add_u64 v[140:141], v[140:141], 0, s[34:35]
	s_add_i32 m0, s38, 0x14400
	s_nop 0
	global_load_lds_dwordx4 v[210:211], off
	s_add_i32 m0, s39, 0x14400
	s_nop 0
	global_load_lds_dwordx4 v[212:213], off
	s_add_i32 m0, s40, 0x14400
	s_nop 0
	global_load_lds_dwordx4 v[214:215], off
	s_add_i32 m0, s37, 0x14400
	s_nop 0
	global_load_lds_dwordx4 v[140:141], off
	global_load_dwordx4 v[4:7], v200, s[8:9]
	global_load_dwordx4 v[8:11], v201, s[8:9]
	global_load_dwordx4 v[12:15], v202, s[8:9]
	global_load_dwordx4 v[16:19], v203, s[8:9]
	global_load_dwordx4 v[20:23], v204, s[8:9]
	global_load_dwordx4 v[24:27], v205, s[8:9]
	global_load_dwordx4 v[28:31], v206, s[8:9]
	global_load_dwordx4 v[32:35], v207, s[8:9]
	s_add_u32 s8, s8, s34
	s_addc_u32 s9, s9, 0
	global_load_dwordx4 v[36:39], v200, s[8:9]
	global_load_dwordx4 v[40:43], v201, s[8:9]
	global_load_dwordx4 v[44:47], v202, s[8:9]
	global_load_dwordx4 v[48:51], v203, s[8:9]
	global_load_dwordx4 v[52:55], v204, s[8:9]
	global_load_dwordx4 v[56:59], v205, s[8:9]
	global_load_dwordx4 v[60:63], v206, s[8:9]
	global_load_dwordx4 v[64:67], v207, s[8:9]
	s_add_u32 s8, s8, s34
	s_addc_u32 s9, s9, 0
	s_waitcnt vmcnt(8)
	s_barrier
; __device__ __forceinline__ void hg_seq(const Frame& F, unsigned char* ws, const float* s0, float* sout, float* Og, int seq, bool sample, int vs_base, int nvs) {
;     ...
;     if (sample && active) {
; #pragma unroll
;         for (int kb = 0; kb < 8; ++kb)
; #pragma unroll
;             for (int i = 0; i < 4; ++i) S[kb][i] = s0[((size_t)seq * 128 + 16 * kb + 4 * q + i) * 128 + 16 * vs + r];
;     } else {
	v_cndmask_b32_e64 v145, v4, v5, s[42:43]
	v_cndmask_b32_e64 v147, v6, v7, s[42:43]
	s_nop 1
	v_mov_b32_dpp v146, v145 quad_perm:[1,0,3,2] row_mask:0xf bank_mask:0xf
	v_mov_b32_dpp v156, v147 quad_perm:[1,0,3,2] row_mask:0xf bank_mask:0xf
	v_cndmask_b32_e64 v5, v5, v146, s[42:43]
	v_cndmask_b32_e64 v4, v146, v4, s[42:43]
	v_cndmask_b32_e64 v7, v7, v156, s[42:43]
	v_cndmask_b32_e64 v6, v156, v6, s[42:43]
	v_cndmask_b32_e64 v145, v4, v6, s[44:45]
	v_cndmask_b32_e64 v147, v5, v7, s[44:45]
	s_nop 1
	v_mov_b32_dpp v146, v145 quad_perm:[2,3,0,1] row_mask:0xf bank_mask:0xf
	v_mov_b32_dpp v156, v147 quad_perm:[2,3,0,1] row_mask:0xf bank_mask:0xf
	v_cndmask_b32_e64 v6, v6, v146, s[44:45]
	v_cndmask_b32_e64 v4, v146, v4, s[44:45]
	v_cndmask_b32_e64 v7, v7, v156, s[44:45]
	v_cndmask_b32_e64 v5, v156, v5, s[44:45]
	v_cndmask_b32_e64 v145, v8, v9, s[42:43]
	v_cndmask_b32_e64 v147, v10, v11, s[42:43]
	s_nop 1
	v_mov_b32_dpp v146, v145 quad_perm:[1,0,3,2] row_mask:0xf bank_mask:0xf
	v_mov_b32_dpp v156, v147 quad_perm:[1,0,3,2] row_mask:0xf bank_mask:0xf
	v_cndmask_b32_e64 v9, v9, v146, s[42:43]
	v_cndmask_b32_e64 v8, v146, v8, s[42:43]
	v_cndmask_b32_e64 v11, v11, v156, s[42:43]
	v_cndmask_b32_e64 v10, v156, v10, s[42:43]
	v_cndmask_b32_e64 v145, v8, v10, s[44:45]
	v_cndmask_b32_e64 v147, v9, v11, s[44:45]
	s_nop 1
	v_mov_b32_dpp v146, v145 quad_perm:[2,3,0,1] row_mask:0xf bank_mask:0xf
	v_mov_b32_dpp v156, v147 quad_perm:[2,3,0,1] row_mask:0xf bank_mask:0xf
	v_cndmask_b32_e64 v10, v10, v146, s[44:45]
	v_cndmask_b32_e64 v8, v146, v8, s[44:45]
	v_cndmask_b32_e64 v11, v11, v156, s[44:45]
	v_cndmask_b32_e64 v9, v156, v9, s[44:45]
	v_cndmask_b32_e64 v145, v12, v13, s[42:43]
	v_cndmask_b32_e64 v147, v14, v15, s[42:43]
	s_nop 1
	v_mov_b32_dpp v146, v145 quad_perm:[1,0,3,2] row_mask:0xf bank_mask:0xf
	v_mov_b32_dpp v156, v147 quad_perm:[1,0,3,2] row_mask:0xf bank_mask:0xf
	v_cndmask_b32_e64 v13, v13, v146, s[42:43]
	v_cndmask_b32_e64 v12, v146, v12, s[42:43]
	v_cndmask_b32_e64 v15, v15, v156, s[42:43]
	v_cndmask_b32_e64 v14, v156, v14, s[42:43]
	v_cndmask_b32_e64 v145, v12, v14, s[44:45]
	v_cndmask_b32_e64 v147, v13, v15, s[44:45]
	s_nop 1
	v_mov_b32_dpp v146, v145 quad_perm:[2,3,0,1] row_mask:0xf bank_mask:0xf
	v_mov_b32_dpp v156, v147 quad_perm:[2,3,0,1] row_mask:0xf bank_mask:0xf
	v_cndmask_b32_e64 v14, v14, v146, s[44:45]
	v_cndmask_b32_e64 v12, v146, v12, s[44:45]
	v_cndmask_b32_e64 v15, v15, v156, s[44:45]
	v_cndmask_b32_e64 v13, v156, v13, s[44:45]
	v_cndmask_b32_e64 v145, v16, v17, s[42:43]
	v_cndmask_b32_e64 v147, v18, v19, s[42:43]
	s_nop 1
	v_mov_b32_dpp v146, v145 quad_perm:[1,0,3,2] row_mask:0xf bank_mask:0xf
	v_mov_b32_dpp v156, v147 quad_perm:[1,0,3,2] row_mask:0xf bank_mask:0xf
	v_cndmask_b32_e64 v17, v17, v146, s[42:43]
	v_cndmask_b32_e64 v16, v146, v16, s[42:43]
	v_cndmask_b32_e64 v19, v19, v156, s[42:43]
	v_cndmask_b32_e64 v18, v156, v18, s[42:43]
	v_cndmask_b32_e64 v145, v16, v18, s[44:45]
	v_cndmask_b32_e64 v147, v17, v19, s[44:45]
	s_nop 1
	v_mov_b32_dpp v146, v145 quad_perm:[2,3,0,1] row_mask:0xf bank_mask:0xf
	v_mov_b32_dpp v156, v147 quad_perm:[2,3,0,1] row_mask:0xf bank_mask:0xf
	v_cndmask_b32_e64 v18, v18, v146, s[44:45]
	v_cndmask_b32_e64 v16, v146, v16, s[44:45]
	v_cndmask_b32_e64 v19, v19, v156, s[44:45]
	v_cndmask_b32_e64 v17, v156, v17, s[44:45]
	v_cndmask_b32_e64 v145, v20, v21, s[42:43]
	v_cndmask_b32_e64 v147, v22, v23, s[42:43]
	s_nop 1
	v_mov_b32_dpp v146, v145 quad_perm:[1,0,3,2] row_mask:0xf bank_mask:0xf
	v_mov_b32_dpp v156, v147 quad_perm:[1,0,3,2] row_mask:0xf bank_mask:0xf
	v_cndmask_b32_e64 v21, v21, v146, s[42:43]
	v_cndmask_b32_e64 v20, v146, v20, s[42:43]
	v_cndmask_b32_e64 v23, v23, v156, s[42:43]
	v_cndmask_b32_e64 v22, v156, v22, s[42:43]
	v_cndmask_b32_e64 v145, v20, v22, s[44:45]
	v_cndmask_b32_e64 v147, v21, v23, s[44:45]
	s_nop 1
	v_mov_b32_dpp v146, v145 quad_perm:[2,3,0,1] row_mask:0xf bank_mask:0xf
	v_mov_b32_dpp v156, v147 quad_perm:[2,3,0,1] row_mask:0xf bank_mask:0xf
	v_cndmask_b32_e64 v22, v22, v146, s[44:45]
	v_cndmask_b32_e64 v20, v146, v20, s[44:45]
	v_cndmask_b32_e64 v23, v23, v156, s[44:45]
	v_cndmask_b32_e64 v21, v156, v21, s[44:45]
	v_cndmask_b32_e64 v145, v24, v25, s[42:43]
	v_cndmask_b32_e64 v147, v26, v27, s[42:43]
	s_nop 1
	v_mov_b32_dpp v146, v145 quad_perm:[1,0,3,2] row_mask:0xf bank_mask:0xf
	v_mov_b32_dpp v156, v147 quad_perm:[1,0,3,2] row_mask:0xf bank_mask:0xf
	v_cndmask_b32_e64 v25, v25, v146, s[42:43]
	v_cndmask_b32_e64 v24, v146, v24, s[42:43]
	v_cndmask_b32_e64 v27, v27, v156, s[42:43]
	v_cndmask_b32_e64 v26, v156, v26, s[42:43]
	v_cndmask_b32_e64 v145, v24, v26, s[44:45]
	v_cndmask_b32_e64 v147, v25, v27, s[44:45]
	s_nop 1
	v_mov_b32_dpp v146, v145 quad_perm:[2,3,0,1] row_mask:0xf bank_mask:0xf
	v_mov_b32_dpp v156, v147 quad_perm:[2,3,0,1] row_mask:0xf bank_mask:0xf
	v_cndmask_b32_e64 v26, v26, v146, s[44:45]
	v_cndmask_b32_e64 v24, v146, v24, s[44:45]
	v_cndmask_b32_e64 v27, v27, v156, s[44:45]
	v_cndmask_b32_e64 v25, v156, v25, s[44:45]
	v_cndmask_b32_e64 v145, v28, v29, s[42:43]
	v_cndmask_b32_e64 v147, v30, v31, s[42:43]
	s_nop 1
	v_mov_b32_dpp v146, v145 quad_perm:[1,0,3,2] row_mask:0xf bank_mask:0xf
	v_mov_b32_dpp v156, v147 quad_perm:[1,0,3,2] row_mask:0xf bank_mask:0xf
	v_cndmask_b32_e64 v29, v29, v146, s[42:43]
	v_cndmask_b32_e64 v28, v146, v28, s[42:43]
	v_cndmask_b32_e64 v31, v31, v156, s[42:43]
	v_cndmask_b32_e64 v30, v156, v30, s[42:43]
	v_cndmask_b32_e64 v145, v28, v30, s[44:45]
	v_cndmask_b32_e64 v147, v29, v31, s[44:45]
	s_nop 1
	v_mov_b32_dpp v146, v145 quad_perm:[2,3,0,1] row_mask:0xf bank_mask:0xf
	v_mov_b32_dpp v156, v147 quad_perm:[2,3,0,1] row_mask:0xf bank_mask:0xf
; #define LAS __attribute__((address_space(3)))
; __device__ __forceinline__ unsigned pk2(float lo, float hi) { const f32x2_t_ v = {lo, hi}; return __builtin_bit_cast(unsigned, __builtin_convertvector(v, bf16x2_t_)); }
; __device__ __forceinline__ void hg_chunk(const LAS unsigned char* sl, f32x4 (&S)[8], float* Orow, int nvalid, int vs, int lane) {
;     const int r = lane & 15, q = lane >> 4;
;     const bf16x8 vfr = *(const LAS bf16x8*)(sl + 16384 + ((vs * 64 + lane) << 4));
;     f32x4 o0 = {0.f, 0.f, 0.f, 0.f}, o1 = {0.f, 0.f, 0.f, 0.f};
;     { const bf16x8 s0 = *(const LAS bf16x8*)(sl + 24576 + (lane << 4)), s1 = *(const LAS bf16x8*)(sl + 24576 + ((64 + lane) << 4));
;       o0 = __builtin_amdgcn_mfma_f32_16x16x32_bf16(s0, vfr, o0, 0, 0, 0); o1 = __builtin_amdgcn_mfma_f32_16x16x32_bf16(s1, vfr, o1, 0, 0, 0); }
; #pragma unroll
;     for (int m = 0; m < 4; ++m) {
;         v4u sw; sw.x = pk2(S[2 * m][0], S[2 * m][1]); sw.y = pk2(S[2 * m][2], S[2 * m][3]); sw.z = pk2(S[2 * m + 1][0], S[2 * m + 1][1]); sw.w = pk2(S[2 * m + 1][2], S[2 * m + 1][3]);
;         const bf16x8 sb = __builtin_bit_cast(bf16x8, sw);
;         const bf16x8 a0 = *(const LAS bf16x8*)(sl + ((m * 64 + lane) << 4)), a1 = *(const LAS bf16x8*)(sl + (((4 + m) * 64 + lane) << 4));
;         o0 = __builtin_amdgcn_mfma_f32_16x16x32_bf16(a0, sb, o0, 0, 0, 0); o1 = __builtin_amdgcn_mfma_f32_16x16x32_bf16(a1, sb, o1, 0, 0, 0);
;     }
; #pragma unroll
;     for (int i = 0; i < 4; ++i) { const int c0 = 4 * q + i;
;         if (c0 < nvalid) Orow[(size_t)c0 * DA + 16 * vs + r] = o0[i];
;         if (c0 + 16 < nvalid) Orow[(size_t)(c0 + 16) * DA + 16 * vs + r] = o1[i]; }
; #pragma unroll
;     for (int kb = 0; kb < 8; ++kb) { const f32x4 d = *(const LAS f32x4*)(sl + 26624 + ((16 * kb + 4 * q) << 2));
;         const bf16x8 ke = *(const LAS bf16x8*)(sl + 8192 + ((kb * 64 + lane) << 4));
;         S[kb] = __builtin_amdgcn_mfma_f32_16x16x32_bf16(ke, vfr, S[kb] * d, 0, 0, 0); }
; __device__ __forceinline__ void hg_seq(const Frame& F, unsigned char* ws, const float* s0, float* sout, float* Og, int seq, bool sample, int vs_base, int nvs) {
;     ...
;     if (sample && active) {
; #pragma unroll
;         for (int kb = 0; kb < 8; ++kb)
; #pragma unroll
;             for (int i = 0; i < 4; ++i) S[kb][i] = s0[((size_t)seq * 128 + 16 * kb + 4 * q + i) * 128 + 16 * vs + r];
;     } else {
	v_cndmask_b32_e64 v30, v30, v146, s[44:45]
	v_cndmask_b32_e64 v28, v146, v28, s[44:45]
	v_cndmask_b32_e64 v31, v31, v156, s[44:45]
	v_cndmask_b32_e64 v29, v156, v29, s[44:45]
	v_cndmask_b32_e64 v145, v32, v33, s[42:43]
	v_cndmask_b32_e64 v147, v34, v35, s[42:43]
	s_nop 1
	v_mov_b32_dpp v146, v145 quad_perm:[1,0,3,2] row_mask:0xf bank_mask:0xf
	v_mov_b32_dpp v156, v147 quad_perm:[1,0,3,2] row_mask:0xf bank_mask:0xf
	v_cndmask_b32_e64 v33, v33, v146, s[42:43]
	v_cndmask_b32_e64 v32, v146, v32, s[42:43]
	v_cndmask_b32_e64 v35, v35, v156, s[42:43]
	v_cndmask_b32_e64 v34, v156, v34, s[42:43]
	v_cndmask_b32_e64 v145, v32, v34, s[44:45]
	v_cndmask_b32_e64 v147, v33, v35, s[44:45]
	s_nop 1
	v_mov_b32_dpp v146, v145 quad_perm:[2,3,0,1] row_mask:0xf bank_mask:0xf
	v_mov_b32_dpp v156, v147 quad_perm:[2,3,0,1] row_mask:0xf bank_mask:0xf
	v_cndmask_b32_e64 v34, v34, v146, s[44:45]
	v_cndmask_b32_e64 v32, v146, v32, s[44:45]
	v_cndmask_b32_e64 v35, v35, v156, s[44:45]
	v_cndmask_b32_e64 v33, v156, v33, s[44:45]
	v_mov_b32_e32 v1, v142
	v_mov_b32_e32 v2, v143
	v_mov_b32_e32 v3, v144
	ds_read_b128 v[164:167], v3 offset:26624
	ds_read_b128 v[168:171], v3 offset:26688
	ds_read_b128 v[172:175], v3 offset:26752
	ds_read_b128 v[176:179], v3 offset:26816
	ds_read_b128 v[180:183], v3 offset:26880
	ds_read_b128 v[184:187], v3 offset:26944
	ds_read_b128 v[148:151], v3 offset:27008
	ds_read_b128 v[152:155], v3 offset:27072
	ds_read_b128 v[84:87], v2 offset:16384
	ds_read_b128 v[88:91], v1 offset:24576
	ds_read_b128 v[92:95], v1 offset:0
	ds_read_b128 v[96:99], v1 offset:1024
	ds_read_b128 v[100:103], v1 offset:2048
	ds_read_b128 v[104:107], v1 offset:3072
	v_cvt_pk_bf16_f32 v68, v4, v5
	v_cvt_pk_bf16_f32 v69, v6, v7
	v_cvt_pk_bf16_f32 v70, v8, v9
	v_cvt_pk_bf16_f32 v71, v10, v11
	v_cvt_pk_bf16_f32 v72, v12, v13
	v_cvt_pk_bf16_f32 v73, v14, v15
	v_cvt_pk_bf16_f32 v74, v16, v17
	v_cvt_pk_bf16_f32 v75, v18, v19
	v_cvt_pk_bf16_f32 v76, v20, v21
	v_cvt_pk_bf16_f32 v77, v22, v23
	v_cvt_pk_bf16_f32 v78, v24, v25
	v_cvt_pk_bf16_f32 v79, v26, v27
	v_cvt_pk_bf16_f32 v80, v28, v29
	v_cvt_pk_bf16_f32 v81, v30, v31
	v_cvt_pk_bf16_f32 v82, v32, v33
	v_cvt_pk_bf16_f32 v83, v34, v35
	s_waitcnt lgkmcnt(6)
	v_pk_mul_f32 v[4:5], v[4:5], v[164:165]
	v_pk_mul_f32 v[6:7], v[6:7], v[166:167]
	v_pk_mul_f32 v[8:9], v[8:9], v[168:169]
	v_pk_mul_f32 v[10:11], v[10:11], v[170:171]
	v_pk_mul_f32 v[12:13], v[12:13], v[172:173]
	v_pk_mul_f32 v[14:15], v[14:15], v[174:175]
	v_pk_mul_f32 v[16:17], v[16:17], v[176:177]
	v_pk_mul_f32 v[18:19], v[18:19], v[178:179]
	v_pk_mul_f32 v[20:21], v[20:21], v[180:181]
	v_pk_mul_f32 v[22:23], v[22:23], v[182:183]
	v_pk_mul_f32 v[24:25], v[24:25], v[184:185]
	v_pk_mul_f32 v[26:27], v[26:27], v[186:187]
	v_pk_mul_f32 v[28:29], v[28:29], v[148:149]
	v_pk_mul_f32 v[30:31], v[30:31], v[150:151]
	v_pk_mul_f32 v[32:33], v[32:33], v[152:153]
	v_pk_mul_f32 v[34:35], v[34:35], v[154:155]
	ds_read_b128 v[108:111], v1 offset:8192
	ds_read_b128 v[112:115], v1 offset:9216
	ds_read_b128 v[116:119], v1 offset:10240
	ds_read_b128 v[120:123], v1 offset:11264
	ds_read_b128 v[124:127], v1 offset:12288
	ds_read_b128 v[128:131], v1 offset:13312
	ds_read_b128 v[132:135], v1 offset:14336
	ds_read_b128 v[136:139], v1 offset:15360
	s_waitcnt lgkmcnt(12)
	v_mfma_f32_16x16x32_bf16 v[196:199], v[88:91], v[84:87], 0
	s_waitcnt lgkmcnt(11)
	v_mfma_f32_16x16x32_bf16 v[196:199], v[92:95], v[68:71], v[196:199]
	s_waitcnt lgkmcnt(10)
	v_mfma_f32_16x16x32_bf16 v[196:199], v[96:99], v[72:75], v[196:199]
	s_waitcnt lgkmcnt(9)
	v_mfma_f32_16x16x32_bf16 v[196:199], v[100:103], v[76:79], v[196:199]
	s_waitcnt lgkmcnt(8)
	v_mfma_f32_16x16x32_bf16 v[196:199], v[104:107], v[80:83], v[196:199]
	s_waitcnt lgkmcnt(7)
	v_mfma_f32_16x16x32_bf16 v[4:7], v[108:111], v[84:87], v[4:7]
	s_waitcnt lgkmcnt(6)
	v_mfma_f32_16x16x32_bf16 v[8:11], v[112:115], v[84:87], v[8:11]
	s_waitcnt lgkmcnt(5)
	v_mfma_f32_16x16x32_bf16 v[12:15], v[116:119], v[84:87], v[12:15]
	s_waitcnt lgkmcnt(4)
	v_mfma_f32_16x16x32_bf16 v[16:19], v[120:123], v[84:87], v[16:19]
	s_waitcnt lgkmcnt(3)
	v_mfma_f32_16x16x32_bf16 v[20:23], v[124:127], v[84:87], v[20:23]
	s_waitcnt lgkmcnt(2)
	v_mfma_f32_16x16x32_bf16 v[24:27], v[128:131], v[84:87], v[24:27]
	s_waitcnt lgkmcnt(1)
	v_mfma_f32_16x16x32_bf16 v[28:31], v[132:135], v[84:87], v[28:31]
	s_waitcnt lgkmcnt(0)
; #define LAS __attribute__((address_space(3)))
; __device__ __forceinline__ void hg_chunk(const LAS unsigned char* sl, f32x4 (&S)[8], float* Orow, int nvalid, int vs, int lane) {
;     ...
;     for (int i = 0; i < 4; ++i) { const int c0 = 4 * q + i;
;         if (c0 < nvalid) Orow[(size_t)c0 * DA + 16 * vs + r] = o0[i];
;         if (c0 + 16 < nvalid) Orow[(size_t)(c0 + 16) * DA + 16 * vs + r] = o1[i]; }
; #pragma unroll
;     for (int kb = 0; kb < 8; ++kb) { const f32x4 d = *(const LAS f32x4*)(sl + 26624 + ((16 * kb + 4 * q) << 2));
;         const bf16x8 ke = *(const LAS bf16x8*)(sl + 8192 + ((kb * 64 + lane) << 4));
;         S[kb] = __builtin_amdgcn_mfma_f32_16x16x32_bf16(ke, vfr, S[kb] * d, 0, 0, 0); }
; __device__ __forceinline__ void hg_seq(const Frame& F, unsigned char* ws, const float* s0, float* sout, float* Og, int seq, bool sample, int vs_base, int nvs) {
;     ...
;     if (active) {
; #pragma unroll
;     for (int kb = 0; kb < 8; ++kb)
; #pragma unroll
;         for (int i = 0; i < 4; ++i) sout[((size_t)seq * 128 + 16 * kb + 4 * q + i) * 128 + 16 * vs + r] = S[kb][i];
;     }
	v_mfma_f32_16x16x32_bf16 v[32:35], v[136:139], v[84:87], v[32:35]
	s_mov_b32 exec_hi, 0
	global_store_dword v208, v196, s[12:13]
	global_store_dword v208, v197, s[12:13] offset:2048
	global_store_dword v209, v198, s[12:13]
	global_store_dword v209, v199, s[12:13] offset:2048
	s_mov_b64 exec, -1
	s_add_u32 s12, s12, 0x80000
	s_addc_u32 s13, s13, 0
	s_nop 7
	v_cndmask_b32_e64 v145, v4, v5, s[42:43]
	v_cndmask_b32_e64 v147, v6, v7, s[42:43]
	s_nop 1
	v_mov_b32_dpp v146, v145 quad_perm:[1,0,3,2] row_mask:0xf bank_mask:0xf
	v_mov_b32_dpp v156, v147 quad_perm:[1,0,3,2] row_mask:0xf bank_mask:0xf
	v_cndmask_b32_e64 v5, v5, v146, s[42:43]
	v_cndmask_b32_e64 v4, v146, v4, s[42:43]
	v_cndmask_b32_e64 v7, v7, v156, s[42:43]
	v_cndmask_b32_e64 v6, v156, v6, s[42:43]
	v_cndmask_b32_e64 v145, v4, v6, s[44:45]
	v_cndmask_b32_e64 v147, v5, v7, s[44:45]
	s_nop 1
	v_mov_b32_dpp v146, v145 quad_perm:[2,3,0,1] row_mask:0xf bank_mask:0xf
	v_mov_b32_dpp v156, v147 quad_perm:[2,3,0,1] row_mask:0xf bank_mask:0xf
	v_cndmask_b32_e64 v6, v6, v146, s[44:45]
	v_cndmask_b32_e64 v4, v146, v4, s[44:45]
	v_cndmask_b32_e64 v7, v7, v156, s[44:45]
	v_cndmask_b32_e64 v5, v156, v5, s[44:45]
	v_cndmask_b32_e64 v145, v8, v9, s[42:43]
	v_cndmask_b32_e64 v147, v10, v11, s[42:43]
	s_nop 1
	v_mov_b32_dpp v146, v145 quad_perm:[1,0,3,2] row_mask:0xf bank_mask:0xf
	v_mov_b32_dpp v156, v147 quad_perm:[1,0,3,2] row_mask:0xf bank_mask:0xf
	v_cndmask_b32_e64 v9, v9, v146, s[42:43]
	v_cndmask_b32_e64 v8, v146, v8, s[42:43]
	v_cndmask_b32_e64 v11, v11, v156, s[42:43]
	v_cndmask_b32_e64 v10, v156, v10, s[42:43]
	v_cndmask_b32_e64 v145, v8, v10, s[44:45]
	v_cndmask_b32_e64 v147, v9, v11, s[44:45]
	s_nop 1
	v_mov_b32_dpp v146, v145 quad_perm:[2,3,0,1] row_mask:0xf bank_mask:0xf
	v_mov_b32_dpp v156, v147 quad_perm:[2,3,0,1] row_mask:0xf bank_mask:0xf
	v_cndmask_b32_e64 v10, v10, v146, s[44:45]
	v_cndmask_b32_e64 v8, v146, v8, s[44:45]
	v_cndmask_b32_e64 v11, v11, v156, s[44:45]
	v_cndmask_b32_e64 v9, v156, v9, s[44:45]
	v_cndmask_b32_e64 v145, v12, v13, s[42:43]
	v_cndmask_b32_e64 v147, v14, v15, s[42:43]
	s_nop 1
	v_mov_b32_dpp v146, v145 quad_perm:[1,0,3,2] row_mask:0xf bank_mask:0xf
	v_mov_b32_dpp v156, v147 quad_perm:[1,0,3,2] row_mask:0xf bank_mask:0xf
	v_cndmask_b32_e64 v13, v13, v146, s[42:43]
	v_cndmask_b32_e64 v12, v146, v12, s[42:43]
	v_cndmask_b32_e64 v15, v15, v156, s[42:43]
	v_cndmask_b32_e64 v14, v156, v14, s[42:43]
	v_cndmask_b32_e64 v145, v12, v14, s[44:45]
	v_cndmask_b32_e64 v147, v13, v15, s[44:45]
	s_nop 1
	v_mov_b32_dpp v146, v145 quad_perm:[2,3,0,1] row_mask:0xf bank_mask:0xf
	v_mov_b32_dpp v156, v147 quad_perm:[2,3,0,1] row_mask:0xf bank_mask:0xf
	v_cndmask_b32_e64 v14, v14, v146, s[44:45]
	v_cndmask_b32_e64 v12, v146, v12, s[44:45]
	v_cndmask_b32_e64 v15, v15, v156, s[44:45]
	v_cndmask_b32_e64 v13, v156, v13, s[44:45]
	v_cndmask_b32_e64 v145, v16, v17, s[42:43]
	v_cndmask_b32_e64 v147, v18, v19, s[42:43]
	s_nop 1
	v_mov_b32_dpp v146, v145 quad_perm:[1,0,3,2] row_mask:0xf bank_mask:0xf
	v_mov_b32_dpp v156, v147 quad_perm:[1,0,3,2] row_mask:0xf bank_mask:0xf
	v_cndmask_b32_e64 v17, v17, v146, s[42:43]
	v_cndmask_b32_e64 v16, v146, v16, s[42:43]
	v_cndmask_b32_e64 v19, v19, v156, s[42:43]
	v_cndmask_b32_e64 v18, v156, v18, s[42:43]
	v_cndmask_b32_e64 v145, v16, v18, s[44:45]
	v_cndmask_b32_e64 v147, v17, v19, s[44:45]
	s_nop 1
	v_mov_b32_dpp v146, v145 quad_perm:[2,3,0,1] row_mask:0xf bank_mask:0xf
	v_mov_b32_dpp v156, v147 quad_perm:[2,3,0,1] row_mask:0xf bank_mask:0xf
	v_cndmask_b32_e64 v18, v18, v146, s[44:45]
	v_cndmask_b32_e64 v16, v146, v16, s[44:45]
	v_cndmask_b32_e64 v19, v19, v156, s[44:45]
	v_cndmask_b32_e64 v17, v156, v17, s[44:45]
	v_cndmask_b32_e64 v145, v20, v21, s[42:43]
	v_cndmask_b32_e64 v147, v22, v23, s[42:43]
	s_nop 1
	v_mov_b32_dpp v146, v145 quad_perm:[1,0,3,2] row_mask:0xf bank_mask:0xf
	v_mov_b32_dpp v156, v147 quad_perm:[1,0,3,2] row_mask:0xf bank_mask:0xf
	v_cndmask_b32_e64 v21, v21, v146, s[42:43]
	v_cndmask_b32_e64 v20, v146, v20, s[42:43]
	v_cndmask_b32_e64 v23, v23, v156, s[42:43]
	v_cndmask_b32_e64 v22, v156, v22, s[42:43]
	v_cndmask_b32_e64 v145, v20, v22, s[44:45]
	v_cndmask_b32_e64 v147, v21, v23, s[44:45]
	s_nop 1
	v_mov_b32_dpp v146, v145 quad_perm:[2,3,0,1] row_mask:0xf bank_mask:0xf
	v_mov_b32_dpp v156, v147 quad_perm:[2,3,0,1] row_mask:0xf bank_mask:0xf
	v_cndmask_b32_e64 v22, v22, v146, s[44:45]
	v_cndmask_b32_e64 v20, v146, v20, s[44:45]
	v_cndmask_b32_e64 v23, v23, v156, s[44:45]
	v_cndmask_b32_e64 v21, v156, v21, s[44:45]
	v_cndmask_b32_e64 v145, v24, v25, s[42:43]
	v_cndmask_b32_e64 v147, v26, v27, s[42:43]
	s_nop 1
	v_mov_b32_dpp v146, v145 quad_perm:[1,0,3,2] row_mask:0xf bank_mask:0xf
	v_mov_b32_dpp v156, v147 quad_perm:[1,0,3,2] row_mask:0xf bank_mask:0xf
	v_cndmask_b32_e64 v25, v25, v146, s[42:43]
	v_cndmask_b32_e64 v24, v146, v24, s[42:43]
	v_cndmask_b32_e64 v27, v27, v156, s[42:43]
	v_cndmask_b32_e64 v26, v156, v26, s[42:43]
	v_cndmask_b32_e64 v145, v24, v26, s[44:45]
	v_cndmask_b32_e64 v147, v25, v27, s[44:45]
	s_nop 1
	v_mov_b32_dpp v146, v145 quad_perm:[2,3,0,1] row_mask:0xf bank_mask:0xf
	v_mov_b32_dpp v156, v147 quad_perm:[2,3,0,1] row_mask:0xf bank_mask:0xf
	v_cndmask_b32_e64 v26, v26, v146, s[44:45]
	v_cndmask_b32_e64 v24, v146, v24, s[44:45]
	v_cndmask_b32_e64 v27, v27, v156, s[44:45]
	v_cndmask_b32_e64 v25, v156, v25, s[44:45]
	v_cndmask_b32_e64 v145, v28, v29, s[42:43]
	v_cndmask_b32_e64 v147, v30, v31, s[42:43]
	s_nop 1
	v_mov_b32_dpp v146, v145 quad_perm:[1,0,3,2] row_mask:0xf bank_mask:0xf
	v_mov_b32_dpp v156, v147 quad_perm:[1,0,3,2] row_mask:0xf bank_mask:0xf
	v_cndmask_b32_e64 v29, v29, v146, s[42:43]
; __device__ __forceinline__ void hg_seq(const Frame& F, unsigned char* ws, const float* s0, float* sout, float* Og, int seq, bool sample, int vs_base, int nvs) {
;     ...
;     if (sample && active) {
; #pragma unroll
;         for (int kb = 0; kb < 8; ++kb)
; #pragma unroll
;             for (int i = 0; i < 4; ++i) S[kb][i] = s0[((size_t)seq * 128 + 16 * kb + 4 * q + i) * 128 + 16 * vs + r];
;     } else {
; #pragma unroll
;         for (int kb = 0; kb < 8; ++kb) S[kb] = (f32x4){0.f, 0.f, 0.f, 0.f};
;     }
;     ...
;     if (active) {
; #pragma unroll
;     for (int kb = 0; kb < 8; ++kb)
; #pragma unroll
;         for (int i = 0; i < 4; ++i) sout[((size_t)seq * 128 + 16 * kb + 4 * q + i) * 128 + 16 * vs + r] = S[kb][i];
;     }
	v_cndmask_b32_e64 v28, v146, v28, s[42:43]
	v_cndmask_b32_e64 v31, v31, v156, s[42:43]
	v_cndmask_b32_e64 v30, v156, v30, s[42:43]
	v_cndmask_b32_e64 v145, v28, v30, s[44:45]
	v_cndmask_b32_e64 v147, v29, v31, s[44:45]
	s_nop 1
	v_mov_b32_dpp v146, v145 quad_perm:[2,3,0,1] row_mask:0xf bank_mask:0xf
	v_mov_b32_dpp v156, v147 quad_perm:[2,3,0,1] row_mask:0xf bank_mask:0xf
	v_cndmask_b32_e64 v30, v30, v146, s[44:45]
	v_cndmask_b32_e64 v28, v146, v28, s[44:45]
	v_cndmask_b32_e64 v31, v31, v156, s[44:45]
	v_cndmask_b32_e64 v29, v156, v29, s[44:45]
	v_cndmask_b32_e64 v145, v32, v33, s[42:43]
	v_cndmask_b32_e64 v147, v34, v35, s[42:43]
	s_nop 1
	v_mov_b32_dpp v146, v145 quad_perm:[1,0,3,2] row_mask:0xf bank_mask:0xf
	v_mov_b32_dpp v156, v147 quad_perm:[1,0,3,2] row_mask:0xf bank_mask:0xf
	v_cndmask_b32_e64 v33, v33, v146, s[42:43]
	v_cndmask_b32_e64 v32, v146, v32, s[42:43]
	v_cndmask_b32_e64 v35, v35, v156, s[42:43]
	v_cndmask_b32_e64 v34, v156, v34, s[42:43]
	v_cndmask_b32_e64 v145, v32, v34, s[44:45]
	v_cndmask_b32_e64 v147, v33, v35, s[44:45]
	s_nop 1
	v_mov_b32_dpp v146, v145 quad_perm:[2,3,0,1] row_mask:0xf bank_mask:0xf
	v_mov_b32_dpp v156, v147 quad_perm:[2,3,0,1] row_mask:0xf bank_mask:0xf
	v_cndmask_b32_e64 v34, v34, v146, s[44:45]
	v_cndmask_b32_e64 v32, v146, v32, s[44:45]
	v_cndmask_b32_e64 v35, v35, v156, s[44:45]
	v_cndmask_b32_e64 v33, v156, v33, s[44:45]
	global_store_dwordx4 v200, v[4:7], s[10:11]
	global_store_dwordx4 v201, v[8:11], s[10:11]
	global_store_dwordx4 v202, v[12:15], s[10:11]
	global_store_dwordx4 v203, v[16:19], s[10:11]
	global_store_dwordx4 v204, v[20:23], s[10:11]
	global_store_dwordx4 v205, v[24:27], s[10:11]
	global_store_dwordx4 v206, v[28:31], s[10:11]
	global_store_dwordx4 v207, v[32:35], s[10:11]
	s_add_u32 s10, s10, s34
	s_addc_u32 s11, s11, 0
	s_waitcnt vmcnt(12)
	global_load_dwordx4 v[4:7], v200, s[8:9]
	global_load_dwordx4 v[8:11], v201, s[8:9]
	global_load_dwordx4 v[12:15], v202, s[8:9]
	global_load_dwordx4 v[16:19], v203, s[8:9]
	global_load_dwordx4 v[20:23], v204, s[8:9]
	global_load_dwordx4 v[24:27], v205, s[8:9]
	global_load_dwordx4 v[28:31], v206, s[8:9]
	global_load_dwordx4 v[32:35], v207, s[8:9]
	s_add_u32 s8, s8, s34
	s_addc_u32 s9, s9, 0
	v_cndmask_b32_e64 v145, v36, v37, s[42:43]
	v_cndmask_b32_e64 v147, v38, v39, s[42:43]
	s_nop 1
	v_mov_b32_dpp v146, v145 quad_perm:[1,0,3,2] row_mask:0xf bank_mask:0xf
	v_mov_b32_dpp v156, v147 quad_perm:[1,0,3,2] row_mask:0xf bank_mask:0xf
	v_cndmask_b32_e64 v37, v37, v146, s[42:43]
	v_cndmask_b32_e64 v36, v146, v36, s[42:43]
	v_cndmask_b32_e64 v39, v39, v156, s[42:43]
	v_cndmask_b32_e64 v38, v156, v38, s[42:43]
	v_cndmask_b32_e64 v145, v36, v38, s[44:45]
	v_cndmask_b32_e64 v147, v37, v39, s[44:45]
	s_nop 1
	v_mov_b32_dpp v146, v145 quad_perm:[2,3,0,1] row_mask:0xf bank_mask:0xf
	v_mov_b32_dpp v156, v147 quad_perm:[2,3,0,1] row_mask:0xf bank_mask:0xf
	v_cndmask_b32_e64 v38, v38, v146, s[44:45]
	v_cndmask_b32_e64 v36, v146, v36, s[44:45]
	v_cndmask_b32_e64 v39, v39, v156, s[44:45]
	v_cndmask_b32_e64 v37, v156, v37, s[44:45]
	v_cndmask_b32_e64 v145, v40, v41, s[42:43]
	v_cndmask_b32_e64 v147, v42, v43, s[42:43]
	s_nop 1
	v_mov_b32_dpp v146, v145 quad_perm:[1,0,3,2] row_mask:0xf bank_mask:0xf
	v_mov_b32_dpp v156, v147 quad_perm:[1,0,3,2] row_mask:0xf bank_mask:0xf
	v_cndmask_b32_e64 v41, v41, v146, s[42:43]
	v_cndmask_b32_e64 v40, v146, v40, s[42:43]
	v_cndmask_b32_e64 v43, v43, v156, s[42:43]
	v_cndmask_b32_e64 v42, v156, v42, s[42:43]
	v_cndmask_b32_e64 v145, v40, v42, s[44:45]
	v_cndmask_b32_e64 v147, v41, v43, s[44:45]
	s_nop 1
	v_mov_b32_dpp v146, v145 quad_perm:[2,3,0,1] row_mask:0xf bank_mask:0xf
	v_mov_b32_dpp v156, v147 quad_perm:[2,3,0,1] row_mask:0xf bank_mask:0xf
	v_cndmask_b32_e64 v42, v42, v146, s[44:45]
	v_cndmask_b32_e64 v40, v146, v40, s[44:45]
	v_cndmask_b32_e64 v43, v43, v156, s[44:45]
	v_cndmask_b32_e64 v41, v156, v41, s[44:45]
	v_cndmask_b32_e64 v145, v44, v45, s[42:43]
	v_cndmask_b32_e64 v147, v46, v47, s[42:43]
	s_nop 1
	v_mov_b32_dpp v146, v145 quad_perm:[1,0,3,2] row_mask:0xf bank_mask:0xf
	v_mov_b32_dpp v156, v147 quad_perm:[1,0,3,2] row_mask:0xf bank_mask:0xf
	v_cndmask_b32_e64 v45, v45, v146, s[42:43]
	v_cndmask_b32_e64 v44, v146, v44, s[42:43]
	v_cndmask_b32_e64 v47, v47, v156, s[42:43]
	v_cndmask_b32_e64 v46, v156, v46, s[42:43]
	v_cndmask_b32_e64 v145, v44, v46, s[44:45]
	v_cndmask_b32_e64 v147, v45, v47, s[44:45]
	s_nop 1
	v_mov_b32_dpp v146, v145 quad_perm:[2,3,0,1] row_mask:0xf bank_mask:0xf
	v_mov_b32_dpp v156, v147 quad_perm:[2,3,0,1] row_mask:0xf bank_mask:0xf
	v_cndmask_b32_e64 v46, v46, v146, s[44:45]
	v_cndmask_b32_e64 v44, v146, v44, s[44:45]
	v_cndmask_b32_e64 v47, v47, v156, s[44:45]
	v_cndmask_b32_e64 v45, v156, v45, s[44:45]
	v_cndmask_b32_e64 v145, v48, v49, s[42:43]
	v_cndmask_b32_e64 v147, v50, v51, s[42:43]
	s_nop 1
	v_mov_b32_dpp v146, v145 quad_perm:[1,0,3,2] row_mask:0xf bank_mask:0xf
	v_mov_b32_dpp v156, v147 quad_perm:[1,0,3,2] row_mask:0xf bank_mask:0xf
	v_cndmask_b32_e64 v49, v49, v146, s[42:43]
	v_cndmask_b32_e64 v48, v146, v48, s[42:43]
	v_cndmask_b32_e64 v51, v51, v156, s[42:43]
	v_cndmask_b32_e64 v50, v156, v50, s[42:43]
	v_cndmask_b32_e64 v145, v48, v50, s[44:45]
	v_cndmask_b32_e64 v147, v49, v51, s[44:45]
	s_nop 1
	v_mov_b32_dpp v146, v145 quad_perm:[2,3,0,1] row_mask:0xf bank_mask:0xf
	v_mov_b32_dpp v156, v147 quad_perm:[2,3,0,1] row_mask:0xf bank_mask:0xf
	v_cndmask_b32_e64 v50, v50, v146, s[44:45]
	v_cndmask_b32_e64 v48, v146, v48, s[44:45]
	v_cndmask_b32_e64 v51, v51, v156, s[44:45]
	v_cndmask_b32_e64 v49, v156, v49, s[44:45]
	v_cndmask_b32_e64 v145, v52, v53, s[42:43]
; #define LAS __attribute__((address_space(3)))
; __device__ __forceinline__ unsigned pk2(float lo, float hi) { const f32x2_t_ v = {lo, hi}; return __builtin_bit_cast(unsigned, __builtin_convertvector(v, bf16x2_t_)); }
; __device__ __forceinline__ void hg_chunk(const LAS unsigned char* sl, f32x4 (&S)[8], float* Orow, int nvalid, int vs, int lane) {
;     const int r = lane & 15, q = lane >> 4;
;     const bf16x8 vfr = *(const LAS bf16x8*)(sl + 16384 + ((vs * 64 + lane) << 4));
;     f32x4 o0 = {0.f, 0.f, 0.f, 0.f}, o1 = {0.f, 0.f, 0.f, 0.f};
;     { const bf16x8 s0 = *(const LAS bf16x8*)(sl + 24576 + (lane << 4)), s1 = *(const LAS bf16x8*)(sl + 24576 + ((64 + lane) << 4));
;       o0 = __builtin_amdgcn_mfma_f32_16x16x32_bf16(s0, vfr, o0, 0, 0, 0); o1 = __builtin_amdgcn_mfma_f32_16x16x32_bf16(s1, vfr, o1, 0, 0, 0); }
; #pragma unroll
;     for (int m = 0; m < 4; ++m) {
;         v4u sw; sw.x = pk2(S[2 * m][0], S[2 * m][1]); sw.y = pk2(S[2 * m][2], S[2 * m][3]); sw.z = pk2(S[2 * m + 1][0], S[2 * m + 1][1]); sw.w = pk2(S[2 * m + 1][2], S[2 * m + 1][3]);
;         const bf16x8 sb = __builtin_bit_cast(bf16x8, sw);
;         const bf16x8 a0 = *(const LAS bf16x8*)(sl + ((m * 64 + lane) << 4)), a1 = *(const LAS bf16x8*)(sl + (((4 + m) * 64 + lane) << 4));
;         o0 = __builtin_amdgcn_mfma_f32_16x16x32_bf16(a0, sb, o0, 0, 0, 0); o1 = __builtin_amdgcn_mfma_f32_16x16x32_bf16(a1, sb, o1, 0, 0, 0);
;     }
; #pragma unroll
;     for (int i = 0; i < 4; ++i) { const int c0 = 4 * q + i;
;         if (c0 < nvalid) Orow[(size_t)c0 * DA + 16 * vs + r] = o0[i];
;         if (c0 + 16 < nvalid) Orow[(size_t)(c0 + 16) * DA + 16 * vs + r] = o1[i]; }
; #pragma unroll
;     for (int kb = 0; kb < 8; ++kb) { const f32x4 d = *(const LAS f32x4*)(sl + 26624 + ((16 * kb + 4 * q) << 2));
;         const bf16x8 ke = *(const LAS bf16x8*)(sl + 8192 + ((kb * 64 + lane) << 4));
;         S[kb] = __builtin_amdgcn_mfma_f32_16x16x32_bf16(ke, vfr, S[kb] * d, 0, 0, 0); }
; __device__ __forceinline__ void hg_seq(const Frame& F, unsigned char* ws, const float* s0, float* sout, float* Og, int seq, bool sample, int vs_base, int nvs) {
;     ...
;     if (sample && active) {
; #pragma unroll
;         for (int kb = 0; kb < 8; ++kb)
; #pragma unroll
;             for (int i = 0; i < 4; ++i) S[kb][i] = s0[((size_t)seq * 128 + 16 * kb + 4 * q + i) * 128 + 16 * vs + r];
;     } else {
	v_cndmask_b32_e64 v147, v54, v55, s[42:43]
	s_nop 1
	v_mov_b32_dpp v146, v145 quad_perm:[1,0,3,2] row_mask:0xf bank_mask:0xf
	v_mov_b32_dpp v156, v147 quad_perm:[1,0,3,2] row_mask:0xf bank_mask:0xf
	v_cndmask_b32_e64 v53, v53, v146, s[42:43]
	v_cndmask_b32_e64 v52, v146, v52, s[42:43]
	v_cndmask_b32_e64 v55, v55, v156, s[42:43]
	v_cndmask_b32_e64 v54, v156, v54, s[42:43]
	v_cndmask_b32_e64 v145, v52, v54, s[44:45]
	v_cndmask_b32_e64 v147, v53, v55, s[44:45]
	s_nop 1
	v_mov_b32_dpp v146, v145 quad_perm:[2,3,0,1] row_mask:0xf bank_mask:0xf
	v_mov_b32_dpp v156, v147 quad_perm:[2,3,0,1] row_mask:0xf bank_mask:0xf
	v_cndmask_b32_e64 v54, v54, v146, s[44:45]
	v_cndmask_b32_e64 v52, v146, v52, s[44:45]
	v_cndmask_b32_e64 v55, v55, v156, s[44:45]
	v_cndmask_b32_e64 v53, v156, v53, s[44:45]
	v_cndmask_b32_e64 v145, v56, v57, s[42:43]
	v_cndmask_b32_e64 v147, v58, v59, s[42:43]
	s_nop 1
	v_mov_b32_dpp v146, v145 quad_perm:[1,0,3,2] row_mask:0xf bank_mask:0xf
	v_mov_b32_dpp v156, v147 quad_perm:[1,0,3,2] row_mask:0xf bank_mask:0xf
	v_cndmask_b32_e64 v57, v57, v146, s[42:43]
	v_cndmask_b32_e64 v56, v146, v56, s[42:43]
	v_cndmask_b32_e64 v59, v59, v156, s[42:43]
	v_cndmask_b32_e64 v58, v156, v58, s[42:43]
	v_cndmask_b32_e64 v145, v56, v58, s[44:45]
	v_cndmask_b32_e64 v147, v57, v59, s[44:45]
	s_nop 1
	v_mov_b32_dpp v146, v145 quad_perm:[2,3,0,1] row_mask:0xf bank_mask:0xf
	v_mov_b32_dpp v156, v147 quad_perm:[2,3,0,1] row_mask:0xf bank_mask:0xf
	v_cndmask_b32_e64 v58, v58, v146, s[44:45]
	v_cndmask_b32_e64 v56, v146, v56, s[44:45]
	v_cndmask_b32_e64 v59, v59, v156, s[44:45]
	v_cndmask_b32_e64 v57, v156, v57, s[44:45]
	v_cndmask_b32_e64 v145, v60, v61, s[42:43]
	v_cndmask_b32_e64 v147, v62, v63, s[42:43]
	s_nop 1
	v_mov_b32_dpp v146, v145 quad_perm:[1,0,3,2] row_mask:0xf bank_mask:0xf
	v_mov_b32_dpp v156, v147 quad_perm:[1,0,3,2] row_mask:0xf bank_mask:0xf
	v_cndmask_b32_e64 v61, v61, v146, s[42:43]
	v_cndmask_b32_e64 v60, v146, v60, s[42:43]
	v_cndmask_b32_e64 v63, v63, v156, s[42:43]
	v_cndmask_b32_e64 v62, v156, v62, s[42:43]
	v_cndmask_b32_e64 v145, v60, v62, s[44:45]
	v_cndmask_b32_e64 v147, v61, v63, s[44:45]
	s_nop 1
	v_mov_b32_dpp v146, v145 quad_perm:[2,3,0,1] row_mask:0xf bank_mask:0xf
	v_mov_b32_dpp v156, v147 quad_perm:[2,3,0,1] row_mask:0xf bank_mask:0xf
	v_cndmask_b32_e64 v62, v62, v146, s[44:45]
	v_cndmask_b32_e64 v60, v146, v60, s[44:45]
	v_cndmask_b32_e64 v63, v63, v156, s[44:45]
	v_cndmask_b32_e64 v61, v156, v61, s[44:45]
	v_cndmask_b32_e64 v145, v64, v65, s[42:43]
	v_cndmask_b32_e64 v147, v66, v67, s[42:43]
	s_nop 1
	v_mov_b32_dpp v146, v145 quad_perm:[1,0,3,2] row_mask:0xf bank_mask:0xf
	v_mov_b32_dpp v156, v147 quad_perm:[1,0,3,2] row_mask:0xf bank_mask:0xf
	v_cndmask_b32_e64 v65, v65, v146, s[42:43]
	v_cndmask_b32_e64 v64, v146, v64, s[42:43]
	v_cndmask_b32_e64 v67, v67, v156, s[42:43]
	v_cndmask_b32_e64 v66, v156, v66, s[42:43]
	v_cndmask_b32_e64 v145, v64, v66, s[44:45]
	v_cndmask_b32_e64 v147, v65, v67, s[44:45]
	s_nop 1
	v_mov_b32_dpp v146, v145 quad_perm:[2,3,0,1] row_mask:0xf bank_mask:0xf
	v_mov_b32_dpp v156, v147 quad_perm:[2,3,0,1] row_mask:0xf bank_mask:0xf
	v_cndmask_b32_e64 v66, v66, v146, s[44:45]
	v_cndmask_b32_e64 v64, v146, v64, s[44:45]
	v_cndmask_b32_e64 v67, v67, v156, s[44:45]
	v_cndmask_b32_e64 v65, v156, v65, s[44:45]
	v_add_u32_e32 v1, 0x6c00, v142
	v_add_u32_e32 v2, 0x6c00, v143
	v_add_u32_e32 v3, 0x6c00, v144
	ds_read_b128 v[164:167], v3 offset:26624
	ds_read_b128 v[168:171], v3 offset:26688
	ds_read_b128 v[172:175], v3 offset:26752
	ds_read_b128 v[176:179], v3 offset:26816
	ds_read_b128 v[180:183], v3 offset:26880
	ds_read_b128 v[184:187], v3 offset:26944
	ds_read_b128 v[148:151], v3 offset:27008
	ds_read_b128 v[152:155], v3 offset:27072
	ds_read_b128 v[84:87], v2 offset:16384
	ds_read_b128 v[88:91], v1 offset:24576
	ds_read_b128 v[92:95], v1 offset:0
	ds_read_b128 v[96:99], v1 offset:1024
	ds_read_b128 v[100:103], v1 offset:2048
	ds_read_b128 v[104:107], v1 offset:3072
	v_cvt_pk_bf16_f32 v68, v36, v37
	v_cvt_pk_bf16_f32 v69, v38, v39
	v_cvt_pk_bf16_f32 v70, v40, v41
	v_cvt_pk_bf16_f32 v71, v42, v43
	v_cvt_pk_bf16_f32 v72, v44, v45
	v_cvt_pk_bf16_f32 v73, v46, v47
	v_cvt_pk_bf16_f32 v74, v48, v49
	v_cvt_pk_bf16_f32 v75, v50, v51
	v_cvt_pk_bf16_f32 v76, v52, v53
	v_cvt_pk_bf16_f32 v77, v54, v55
	v_cvt_pk_bf16_f32 v78, v56, v57
	v_cvt_pk_bf16_f32 v79, v58, v59
	v_cvt_pk_bf16_f32 v80, v60, v61
	v_cvt_pk_bf16_f32 v81, v62, v63
	v_cvt_pk_bf16_f32 v82, v64, v65
	v_cvt_pk_bf16_f32 v83, v66, v67
	s_waitcnt lgkmcnt(6)
	v_pk_mul_f32 v[36:37], v[36:37], v[164:165]
	v_pk_mul_f32 v[38:39], v[38:39], v[166:167]
	v_pk_mul_f32 v[40:41], v[40:41], v[168:169]
	v_pk_mul_f32 v[42:43], v[42:43], v[170:171]
	v_pk_mul_f32 v[44:45], v[44:45], v[172:173]
	v_pk_mul_f32 v[46:47], v[46:47], v[174:175]
	v_pk_mul_f32 v[48:49], v[48:49], v[176:177]
	v_pk_mul_f32 v[50:51], v[50:51], v[178:179]
	v_pk_mul_f32 v[52:53], v[52:53], v[180:181]
	v_pk_mul_f32 v[54:55], v[54:55], v[182:183]
	v_pk_mul_f32 v[56:57], v[56:57], v[184:185]
	v_pk_mul_f32 v[58:59], v[58:59], v[186:187]
	v_pk_mul_f32 v[60:61], v[60:61], v[148:149]
	v_pk_mul_f32 v[62:63], v[62:63], v[150:151]
	v_pk_mul_f32 v[64:65], v[64:65], v[152:153]
	v_pk_mul_f32 v[66:67], v[66:67], v[154:155]
	ds_read_b128 v[108:111], v1 offset:8192
	ds_read_b128 v[112:115], v1 offset:9216
	ds_read_b128 v[116:119], v1 offset:10240
	ds_read_b128 v[120:123], v1 offset:11264
	ds_read_b128 v[124:127], v1 offset:12288
	ds_read_b128 v[128:131], v1 offset:13312
	ds_read_b128 v[132:135], v1 offset:14336
	ds_read_b128 v[136:139], v1 offset:15360
	s_waitcnt lgkmcnt(12)
; #define LAS __attribute__((address_space(3)))
; __device__ __forceinline__ unsigned pk2(float lo, float hi) { const f32x2_t_ v = {lo, hi}; return __builtin_bit_cast(unsigned, __builtin_convertvector(v, bf16x2_t_)); }
; __device__ __forceinline__ void hg_chunk(const LAS unsigned char* sl, f32x4 (&S)[8], float* Orow, int nvalid, int vs, int lane) {
;     ...
;     { const bf16x8 s0 = *(const LAS bf16x8*)(sl + 24576 + (lane << 4)), s1 = *(const LAS bf16x8*)(sl + 24576 + ((64 + lane) << 4));
;       o0 = __builtin_amdgcn_mfma_f32_16x16x32_bf16(s0, vfr, o0, 0, 0, 0); o1 = __builtin_amdgcn_mfma_f32_16x16x32_bf16(s1, vfr, o1, 0, 0, 0); }
; #pragma unroll
;     for (int m = 0; m < 4; ++m) {
;         v4u sw; sw.x = pk2(S[2 * m][0], S[2 * m][1]); sw.y = pk2(S[2 * m][2], S[2 * m][3]); sw.z = pk2(S[2 * m + 1][0], S[2 * m + 1][1]); sw.w = pk2(S[2 * m + 1][2], S[2 * m + 1][3]);
;         const bf16x8 sb = __builtin_bit_cast(bf16x8, sw);
;         const bf16x8 a0 = *(const LAS bf16x8*)(sl + ((m * 64 + lane) << 4)), a1 = *(const LAS bf16x8*)(sl + (((4 + m) * 64 + lane) << 4));
;         o0 = __builtin_amdgcn_mfma_f32_16x16x32_bf16(a0, sb, o0, 0, 0, 0); o1 = __builtin_amdgcn_mfma_f32_16x16x32_bf16(a1, sb, o1, 0, 0, 0);
;     }
; #pragma unroll
;     for (int i = 0; i < 4; ++i) { const int c0 = 4 * q + i;
;         if (c0 < nvalid) Orow[(size_t)c0 * DA + 16 * vs + r] = o0[i];
;         if (c0 + 16 < nvalid) Orow[(size_t)(c0 + 16) * DA + 16 * vs + r] = o1[i]; }
; #pragma unroll
;     for (int kb = 0; kb < 8; ++kb) { const f32x4 d = *(const LAS f32x4*)(sl + 26624 + ((16 * kb + 4 * q) << 2));
;         const bf16x8 ke = *(const LAS bf16x8*)(sl + 8192 + ((kb * 64 + lane) << 4));
;         S[kb] = __builtin_amdgcn_mfma_f32_16x16x32_bf16(ke, vfr, S[kb] * d, 0, 0, 0); }
; __device__ __forceinline__ void hg_seq(const Frame& F, unsigned char* ws, const float* s0, float* sout, float* Og, int seq, bool sample, int vs_base, int nvs) {
;     ...
;     if (active) {
; #pragma unroll
;     for (int kb = 0; kb < 8; ++kb)
; #pragma unroll
;         for (int i = 0; i < 4; ++i) sout[((size_t)seq * 128 + 16 * kb + 4 * q + i) * 128 + 16 * vs + r] = S[kb][i];
;     }
	v_mfma_f32_16x16x32_bf16 v[196:199], v[88:91], v[84:87], 0
	s_waitcnt lgkmcnt(11)
	v_mfma_f32_16x16x32_bf16 v[196:199], v[92:95], v[68:71], v[196:199]
	s_waitcnt lgkmcnt(10)
	v_mfma_f32_16x16x32_bf16 v[196:199], v[96:99], v[72:75], v[196:199]
	s_waitcnt lgkmcnt(9)
	v_mfma_f32_16x16x32_bf16 v[196:199], v[100:103], v[76:79], v[196:199]
	s_waitcnt lgkmcnt(8)
	v_mfma_f32_16x16x32_bf16 v[196:199], v[104:107], v[80:83], v[196:199]
	s_waitcnt lgkmcnt(7)
	v_mfma_f32_16x16x32_bf16 v[36:39], v[108:111], v[84:87], v[36:39]
	s_waitcnt lgkmcnt(6)
	v_mfma_f32_16x16x32_bf16 v[40:43], v[112:115], v[84:87], v[40:43]
	s_waitcnt lgkmcnt(5)
	v_mfma_f32_16x16x32_bf16 v[44:47], v[116:119], v[84:87], v[44:47]
	s_waitcnt lgkmcnt(4)
	v_mfma_f32_16x16x32_bf16 v[48:51], v[120:123], v[84:87], v[48:51]
	s_waitcnt lgkmcnt(3)
	v_mfma_f32_16x16x32_bf16 v[52:55], v[124:127], v[84:87], v[52:55]
	s_waitcnt lgkmcnt(2)
	v_mfma_f32_16x16x32_bf16 v[56:59], v[128:131], v[84:87], v[56:59]
	s_waitcnt lgkmcnt(1)
	v_mfma_f32_16x16x32_bf16 v[60:63], v[132:135], v[84:87], v[60:63]
	s_waitcnt lgkmcnt(0)
	v_mfma_f32_16x16x32_bf16 v[64:67], v[136:139], v[84:87], v[64:67]
	s_mov_b32 exec_hi, 0
	global_store_dword v208, v196, s[12:13]
	global_store_dword v208, v197, s[12:13] offset:2048
	global_store_dword v209, v198, s[12:13]
	global_store_dword v209, v199, s[12:13] offset:2048
	s_mov_b64 exec, -1
	s_add_u32 s12, s12, 0x80000
	s_addc_u32 s13, s13, 0
	s_nop 7
	v_cndmask_b32_e64 v145, v36, v37, s[42:43]
	v_cndmask_b32_e64 v147, v38, v39, s[42:43]
	s_nop 1
	v_mov_b32_dpp v146, v145 quad_perm:[1,0,3,2] row_mask:0xf bank_mask:0xf
	v_mov_b32_dpp v156, v147 quad_perm:[1,0,3,2] row_mask:0xf bank_mask:0xf
	v_cndmask_b32_e64 v37, v37, v146, s[42:43]
	v_cndmask_b32_e64 v36, v146, v36, s[42:43]
	v_cndmask_b32_e64 v39, v39, v156, s[42:43]
	v_cndmask_b32_e64 v38, v156, v38, s[42:43]
	v_cndmask_b32_e64 v145, v36, v38, s[44:45]
	v_cndmask_b32_e64 v147, v37, v39, s[44:45]
	s_nop 1
	v_mov_b32_dpp v146, v145 quad_perm:[2,3,0,1] row_mask:0xf bank_mask:0xf
	v_mov_b32_dpp v156, v147 quad_perm:[2,3,0,1] row_mask:0xf bank_mask:0xf
	v_cndmask_b32_e64 v38, v38, v146, s[44:45]
	v_cndmask_b32_e64 v36, v146, v36, s[44:45]
	v_cndmask_b32_e64 v39, v39, v156, s[44:45]
	v_cndmask_b32_e64 v37, v156, v37, s[44:45]
	v_cndmask_b32_e64 v145, v40, v41, s[42:43]
	v_cndmask_b32_e64 v147, v42, v43, s[42:43]
	s_nop 1
	v_mov_b32_dpp v146, v145 quad_perm:[1,0,3,2] row_mask:0xf bank_mask:0xf
	v_mov_b32_dpp v156, v147 quad_perm:[1,0,3,2] row_mask:0xf bank_mask:0xf
	v_cndmask_b32_e64 v41, v41, v146, s[42:43]
	v_cndmask_b32_e64 v40, v146, v40, s[42:43]
	v_cndmask_b32_e64 v43, v43, v156, s[42:43]
	v_cndmask_b32_e64 v42, v156, v42, s[42:43]
	v_cndmask_b32_e64 v145, v40, v42, s[44:45]
	v_cndmask_b32_e64 v147, v41, v43, s[44:45]
	s_nop 1
	v_mov_b32_dpp v146, v145 quad_perm:[2,3,0,1] row_mask:0xf bank_mask:0xf
	v_mov_b32_dpp v156, v147 quad_perm:[2,3,0,1] row_mask:0xf bank_mask:0xf
	v_cndmask_b32_e64 v42, v42, v146, s[44:45]
	v_cndmask_b32_e64 v40, v146, v40, s[44:45]
	v_cndmask_b32_e64 v43, v43, v156, s[44:45]
	v_cndmask_b32_e64 v41, v156, v41, s[44:45]
	v_cndmask_b32_e64 v145, v44, v45, s[42:43]
	v_cndmask_b32_e64 v147, v46, v47, s[42:43]
	s_nop 1
	v_mov_b32_dpp v146, v145 quad_perm:[1,0,3,2] row_mask:0xf bank_mask:0xf
	v_mov_b32_dpp v156, v147 quad_perm:[1,0,3,2] row_mask:0xf bank_mask:0xf
	v_cndmask_b32_e64 v45, v45, v146, s[42:43]
	v_cndmask_b32_e64 v44, v146, v44, s[42:43]
	v_cndmask_b32_e64 v47, v47, v156, s[42:43]
	v_cndmask_b32_e64 v46, v156, v46, s[42:43]
	v_cndmask_b32_e64 v145, v44, v46, s[44:45]
	v_cndmask_b32_e64 v147, v45, v47, s[44:45]
	s_nop 1
	v_mov_b32_dpp v146, v145 quad_perm:[2,3,0,1] row_mask:0xf bank_mask:0xf
	v_mov_b32_dpp v156, v147 quad_perm:[2,3,0,1] row_mask:0xf bank_mask:0xf
	v_cndmask_b32_e64 v46, v46, v146, s[44:45]
	v_cndmask_b32_e64 v44, v146, v44, s[44:45]
	v_cndmask_b32_e64 v47, v47, v156, s[44:45]
	v_cndmask_b32_e64 v45, v156, v45, s[44:45]
	v_cndmask_b32_e64 v145, v48, v49, s[42:43]
	v_cndmask_b32_e64 v147, v50, v51, s[42:43]
	s_nop 1
	v_mov_b32_dpp v146, v145 quad_perm:[1,0,3,2] row_mask:0xf bank_mask:0xf
	v_mov_b32_dpp v156, v147 quad_perm:[1,0,3,2] row_mask:0xf bank_mask:0xf
	v_cndmask_b32_e64 v49, v49, v146, s[42:43]
	v_cndmask_b32_e64 v48, v146, v48, s[42:43]
	v_cndmask_b32_e64 v51, v51, v156, s[42:43]
	v_cndmask_b32_e64 v50, v156, v50, s[42:43]
	v_cndmask_b32_e64 v145, v48, v50, s[44:45]
	v_cndmask_b32_e64 v147, v49, v51, s[44:45]
	s_nop 1
	v_mov_b32_dpp v146, v145 quad_perm:[2,3,0,1] row_mask:0xf bank_mask:0xf
	v_mov_b32_dpp v156, v147 quad_perm:[2,3,0,1] row_mask:0xf bank_mask:0xf
	v_cndmask_b32_e64 v50, v50, v146, s[44:45]
	v_cndmask_b32_e64 v48, v146, v48, s[44:45]
	v_cndmask_b32_e64 v51, v51, v156, s[44:45]
	v_cndmask_b32_e64 v49, v156, v49, s[44:45]
	v_cndmask_b32_e64 v145, v52, v53, s[42:43]
	v_cndmask_b32_e64 v147, v54, v55, s[42:43]
	s_nop 1
	v_mov_b32_dpp v146, v145 quad_perm:[1,0,3,2] row_mask:0xf bank_mask:0xf
	v_mov_b32_dpp v156, v147 quad_perm:[1,0,3,2] row_mask:0xf bank_mask:0xf
	v_cndmask_b32_e64 v53, v53, v146, s[42:43]
	v_cndmask_b32_e64 v52, v146, v52, s[42:43]
	v_cndmask_b32_e64 v55, v55, v156, s[42:43]
	v_cndmask_b32_e64 v54, v156, v54, s[42:43]
	v_cndmask_b32_e64 v145, v52, v54, s[44:45]
	v_cndmask_b32_e64 v147, v53, v55, s[44:45]
	s_nop 1
	v_mov_b32_dpp v146, v145 quad_perm:[2,3,0,1] row_mask:0xf bank_mask:0xf
	v_mov_b32_dpp v156, v147 quad_perm:[2,3,0,1] row_mask:0xf bank_mask:0xf
	v_cndmask_b32_e64 v54, v54, v146, s[44:45]
	v_cndmask_b32_e64 v52, v146, v52, s[44:45]
	v_cndmask_b32_e64 v55, v55, v156, s[44:45]
	v_cndmask_b32_e64 v53, v156, v53, s[44:45]
; __device__ __forceinline__ void hg_seq(const Frame& F, unsigned char* ws, const float* s0, float* sout, float* Og, int seq, bool sample, int vs_base, int nvs) {
;     ...
;     if (sample && active) {
; #pragma unroll
;         for (int kb = 0; kb < 8; ++kb)
; #pragma unroll
;             for (int i = 0; i < 4; ++i) S[kb][i] = s0[((size_t)seq * 128 + 16 * kb + 4 * q + i) * 128 + 16 * vs + r];
;     } else {
;     ...
;     if (active) {
; #pragma unroll
;     for (int kb = 0; kb < 8; ++kb)
; #pragma unroll
;         for (int i = 0; i < 4; ++i) sout[((size_t)seq * 128 + 16 * kb + 4 * q + i) * 128 + 16 * vs + r] = S[kb][i];
;     }
	v_cndmask_b32_e64 v145, v56, v57, s[42:43]
	v_cndmask_b32_e64 v147, v58, v59, s[42:43]
	s_nop 1
	v_mov_b32_dpp v146, v145 quad_perm:[1,0,3,2] row_mask:0xf bank_mask:0xf
	v_mov_b32_dpp v156, v147 quad_perm:[1,0,3,2] row_mask:0xf bank_mask:0xf
	v_cndmask_b32_e64 v57, v57, v146, s[42:43]
	v_cndmask_b32_e64 v56, v146, v56, s[42:43]
	v_cndmask_b32_e64 v59, v59, v156, s[42:43]
	v_cndmask_b32_e64 v58, v156, v58, s[42:43]
	v_cndmask_b32_e64 v145, v56, v58, s[44:45]
	v_cndmask_b32_e64 v147, v57, v59, s[44:45]
	s_nop 1
	v_mov_b32_dpp v146, v145 quad_perm:[2,3,0,1] row_mask:0xf bank_mask:0xf
	v_mov_b32_dpp v156, v147 quad_perm:[2,3,0,1] row_mask:0xf bank_mask:0xf
	v_cndmask_b32_e64 v58, v58, v146, s[44:45]
	v_cndmask_b32_e64 v56, v146, v56, s[44:45]
	v_cndmask_b32_e64 v59, v59, v156, s[44:45]
	v_cndmask_b32_e64 v57, v156, v57, s[44:45]
	v_cndmask_b32_e64 v145, v60, v61, s[42:43]
	v_cndmask_b32_e64 v147, v62, v63, s[42:43]
	s_nop 1
	v_mov_b32_dpp v146, v145 quad_perm:[1,0,3,2] row_mask:0xf bank_mask:0xf
	v_mov_b32_dpp v156, v147 quad_perm:[1,0,3,2] row_mask:0xf bank_mask:0xf
	v_cndmask_b32_e64 v61, v61, v146, s[42:43]
	v_cndmask_b32_e64 v60, v146, v60, s[42:43]
	v_cndmask_b32_e64 v63, v63, v156, s[42:43]
	v_cndmask_b32_e64 v62, v156, v62, s[42:43]
	v_cndmask_b32_e64 v145, v60, v62, s[44:45]
	v_cndmask_b32_e64 v147, v61, v63, s[44:45]
	s_nop 1
	v_mov_b32_dpp v146, v145 quad_perm:[2,3,0,1] row_mask:0xf bank_mask:0xf
	v_mov_b32_dpp v156, v147 quad_perm:[2,3,0,1] row_mask:0xf bank_mask:0xf
	v_cndmask_b32_e64 v62, v62, v146, s[44:45]
	v_cndmask_b32_e64 v60, v146, v60, s[44:45]
	v_cndmask_b32_e64 v63, v63, v156, s[44:45]
	v_cndmask_b32_e64 v61, v156, v61, s[44:45]
	v_cndmask_b32_e64 v145, v64, v65, s[42:43]
	v_cndmask_b32_e64 v147, v66, v67, s[42:43]
	s_nop 1
	v_mov_b32_dpp v146, v145 quad_perm:[1,0,3,2] row_mask:0xf bank_mask:0xf
	v_mov_b32_dpp v156, v147 quad_perm:[1,0,3,2] row_mask:0xf bank_mask:0xf
	v_cndmask_b32_e64 v65, v65, v146, s[42:43]
	v_cndmask_b32_e64 v64, v146, v64, s[42:43]
	v_cndmask_b32_e64 v67, v67, v156, s[42:43]
	v_cndmask_b32_e64 v66, v156, v66, s[42:43]
	v_cndmask_b32_e64 v145, v64, v66, s[44:45]
	v_cndmask_b32_e64 v147, v65, v67, s[44:45]
	s_nop 1
	v_mov_b32_dpp v146, v145 quad_perm:[2,3,0,1] row_mask:0xf bank_mask:0xf
	v_mov_b32_dpp v156, v147 quad_perm:[2,3,0,1] row_mask:0xf bank_mask:0xf
	v_cndmask_b32_e64 v66, v66, v146, s[44:45]
	v_cndmask_b32_e64 v64, v146, v64, s[44:45]
	v_cndmask_b32_e64 v67, v67, v156, s[44:45]
	v_cndmask_b32_e64 v65, v156, v65, s[44:45]
	global_store_dwordx4 v200, v[36:39], s[10:11]
	global_store_dwordx4 v201, v[40:43], s[10:11]
	global_store_dwordx4 v202, v[44:47], s[10:11]
	global_store_dwordx4 v203, v[48:51], s[10:11]
	global_store_dwordx4 v204, v[52:55], s[10:11]
	global_store_dwordx4 v205, v[56:59], s[10:11]
	global_store_dwordx4 v206, v[60:63], s[10:11]
	global_store_dwordx4 v207, v[64:67], s[10:11]
	s_add_u32 s10, s10, s34
	s_addc_u32 s11, s11, 0
	s_waitcnt vmcnt(12)
	global_load_dwordx4 v[36:39], v200, s[8:9]
	global_load_dwordx4 v[40:43], v201, s[8:9]
	global_load_dwordx4 v[44:47], v202, s[8:9]
	global_load_dwordx4 v[48:51], v203, s[8:9]
	global_load_dwordx4 v[52:55], v204, s[8:9]
	global_load_dwordx4 v[56:59], v205, s[8:9]
	global_load_dwordx4 v[60:63], v206, s[8:9]
	global_load_dwordx4 v[64:67], v207, s[8:9]
	s_add_u32 s8, s8, s34
	s_addc_u32 s9, s9, 0
	v_cndmask_b32_e64 v145, v4, v5, s[42:43]
	v_cndmask_b32_e64 v147, v6, v7, s[42:43]
	s_nop 1
	v_mov_b32_dpp v146, v145 quad_perm:[1,0,3,2] row_mask:0xf bank_mask:0xf
	v_mov_b32_dpp v156, v147 quad_perm:[1,0,3,2] row_mask:0xf bank_mask:0xf
	v_cndmask_b32_e64 v5, v5, v146, s[42:43]
	v_cndmask_b32_e64 v4, v146, v4, s[42:43]
	v_cndmask_b32_e64 v7, v7, v156, s[42:43]
	v_cndmask_b32_e64 v6, v156, v6, s[42:43]
	v_cndmask_b32_e64 v145, v4, v6, s[44:45]
	v_cndmask_b32_e64 v147, v5, v7, s[44:45]
	s_nop 1
	v_mov_b32_dpp v146, v145 quad_perm:[2,3,0,1] row_mask:0xf bank_mask:0xf
	v_mov_b32_dpp v156, v147 quad_perm:[2,3,0,1] row_mask:0xf bank_mask:0xf
	v_cndmask_b32_e64 v6, v6, v146, s[44:45]
	v_cndmask_b32_e64 v4, v146, v4, s[44:45]
	v_cndmask_b32_e64 v7, v7, v156, s[44:45]
	v_cndmask_b32_e64 v5, v156, v5, s[44:45]
	v_cndmask_b32_e64 v145, v8, v9, s[42:43]
	v_cndmask_b32_e64 v147, v10, v11, s[42:43]
	s_nop 1
	v_mov_b32_dpp v146, v145 quad_perm:[1,0,3,2] row_mask:0xf bank_mask:0xf
	v_mov_b32_dpp v156, v147 quad_perm:[1,0,3,2] row_mask:0xf bank_mask:0xf
	v_cndmask_b32_e64 v9, v9, v146, s[42:43]
	v_cndmask_b32_e64 v8, v146, v8, s[42:43]
	v_cndmask_b32_e64 v11, v11, v156, s[42:43]
	v_cndmask_b32_e64 v10, v156, v10, s[42:43]
	v_cndmask_b32_e64 v145, v8, v10, s[44:45]
	v_cndmask_b32_e64 v147, v9, v11, s[44:45]
	s_nop 1
	v_mov_b32_dpp v146, v145 quad_perm:[2,3,0,1] row_mask:0xf bank_mask:0xf
	v_mov_b32_dpp v156, v147 quad_perm:[2,3,0,1] row_mask:0xf bank_mask:0xf
	v_cndmask_b32_e64 v10, v10, v146, s[44:45]
	v_cndmask_b32_e64 v8, v146, v8, s[44:45]
	v_cndmask_b32_e64 v11, v11, v156, s[44:45]
	v_cndmask_b32_e64 v9, v156, v9, s[44:45]
	v_cndmask_b32_e64 v145, v12, v13, s[42:43]
	v_cndmask_b32_e64 v147, v14, v15, s[42:43]
	s_nop 1
	v_mov_b32_dpp v146, v145 quad_perm:[1,0,3,2] row_mask:0xf bank_mask:0xf
	v_mov_b32_dpp v156, v147 quad_perm:[1,0,3,2] row_mask:0xf bank_mask:0xf
	v_cndmask_b32_e64 v13, v13, v146, s[42:43]
	v_cndmask_b32_e64 v12, v146, v12, s[42:43]
	v_cndmask_b32_e64 v15, v15, v156, s[42:43]
	v_cndmask_b32_e64 v14, v156, v14, s[42:43]
	v_cndmask_b32_e64 v145, v12, v14, s[44:45]
	v_cndmask_b32_e64 v147, v13, v15, s[44:45]
	s_nop 1
	v_mov_b32_dpp v146, v145 quad_perm:[2,3,0,1] row_mask:0xf bank_mask:0xf
	v_mov_b32_dpp v156, v147 quad_perm:[2,3,0,1] row_mask:0xf bank_mask:0xf
; #define LAS __attribute__((address_space(3)))
; __device__ __forceinline__ unsigned pk2(float lo, float hi) { const f32x2_t_ v = {lo, hi}; return __builtin_bit_cast(unsigned, __builtin_convertvector(v, bf16x2_t_)); }
; __device__ __forceinline__ void hg_chunk(const LAS unsigned char* sl, f32x4 (&S)[8], float* Orow, int nvalid, int vs, int lane) {
;     const int r = lane & 15, q = lane >> 4;
;     const bf16x8 vfr = *(const LAS bf16x8*)(sl + 16384 + ((vs * 64 + lane) << 4));
;     f32x4 o0 = {0.f, 0.f, 0.f, 0.f}, o1 = {0.f, 0.f, 0.f, 0.f};
;     { const bf16x8 s0 = *(const LAS bf16x8*)(sl + 24576 + (lane << 4)), s1 = *(const LAS bf16x8*)(sl + 24576 + ((64 + lane) << 4));
;       o0 = __builtin_amdgcn_mfma_f32_16x16x32_bf16(s0, vfr, o0, 0, 0, 0); o1 = __builtin_amdgcn_mfma_f32_16x16x32_bf16(s1, vfr, o1, 0, 0, 0); }
; #pragma unroll
;     for (int m = 0; m < 4; ++m) {
;         v4u sw; sw.x = pk2(S[2 * m][0], S[2 * m][1]); sw.y = pk2(S[2 * m][2], S[2 * m][3]); sw.z = pk2(S[2 * m + 1][0], S[2 * m + 1][1]); sw.w = pk2(S[2 * m + 1][2], S[2 * m + 1][3]);
;         const bf16x8 sb = __builtin_bit_cast(bf16x8, sw);
;         const bf16x8 a0 = *(const LAS bf16x8*)(sl + ((m * 64 + lane) << 4)), a1 = *(const LAS bf16x8*)(sl + (((4 + m) * 64 + lane) << 4));
;         o0 = __builtin_amdgcn_mfma_f32_16x16x32_bf16(a0, sb, o0, 0, 0, 0); o1 = __builtin_amdgcn_mfma_f32_16x16x32_bf16(a1, sb, o1, 0, 0, 0);
;     }
; #pragma unroll
;     for (int i = 0; i < 4; ++i) { const int c0 = 4 * q + i;
;         if (c0 < nvalid) Orow[(size_t)c0 * DA + 16 * vs + r] = o0[i];
;         if (c0 + 16 < nvalid) Orow[(size_t)(c0 + 16) * DA + 16 * vs + r] = o1[i]; }
; #pragma unroll
;     for (int kb = 0; kb < 8; ++kb) { const f32x4 d = *(const LAS f32x4*)(sl + 26624 + ((16 * kb + 4 * q) << 2));
;         const bf16x8 ke = *(const LAS bf16x8*)(sl + 8192 + ((kb * 64 + lane) << 4));
;         S[kb] = __builtin_amdgcn_mfma_f32_16x16x32_bf16(ke, vfr, S[kb] * d, 0, 0, 0); }
; __device__ __forceinline__ void hg_seq(const Frame& F, unsigned char* ws, const float* s0, float* sout, float* Og, int seq, bool sample, int vs_base, int nvs) {
;     ...
;     if (sample && active) {
; #pragma unroll
;         for (int kb = 0; kb < 8; ++kb)
; #pragma unroll
;             for (int i = 0; i < 4; ++i) S[kb][i] = s0[((size_t)seq * 128 + 16 * kb + 4 * q + i) * 128 + 16 * vs + r];
;     } else {
	v_cndmask_b32_e64 v14, v14, v146, s[44:45]
	v_cndmask_b32_e64 v12, v146, v12, s[44:45]
	v_cndmask_b32_e64 v15, v15, v156, s[44:45]
	v_cndmask_b32_e64 v13, v156, v13, s[44:45]
	v_cndmask_b32_e64 v145, v16, v17, s[42:43]
	v_cndmask_b32_e64 v147, v18, v19, s[42:43]
	s_nop 1
	v_mov_b32_dpp v146, v145 quad_perm:[1,0,3,2] row_mask:0xf bank_mask:0xf
	v_mov_b32_dpp v156, v147 quad_perm:[1,0,3,2] row_mask:0xf bank_mask:0xf
	v_cndmask_b32_e64 v17, v17, v146, s[42:43]
	v_cndmask_b32_e64 v16, v146, v16, s[42:43]
	v_cndmask_b32_e64 v19, v19, v156, s[42:43]
	v_cndmask_b32_e64 v18, v156, v18, s[42:43]
	v_cndmask_b32_e64 v145, v16, v18, s[44:45]
	v_cndmask_b32_e64 v147, v17, v19, s[44:45]
	s_nop 1
	v_mov_b32_dpp v146, v145 quad_perm:[2,3,0,1] row_mask:0xf bank_mask:0xf
	v_mov_b32_dpp v156, v147 quad_perm:[2,3,0,1] row_mask:0xf bank_mask:0xf
	v_cndmask_b32_e64 v18, v18, v146, s[44:45]
	v_cndmask_b32_e64 v16, v146, v16, s[44:45]
	v_cndmask_b32_e64 v19, v19, v156, s[44:45]
	v_cndmask_b32_e64 v17, v156, v17, s[44:45]
	v_cndmask_b32_e64 v145, v20, v21, s[42:43]
	v_cndmask_b32_e64 v147, v22, v23, s[42:43]
	s_nop 1
	v_mov_b32_dpp v146, v145 quad_perm:[1,0,3,2] row_mask:0xf bank_mask:0xf
	v_mov_b32_dpp v156, v147 quad_perm:[1,0,3,2] row_mask:0xf bank_mask:0xf
	v_cndmask_b32_e64 v21, v21, v146, s[42:43]
	v_cndmask_b32_e64 v20, v146, v20, s[42:43]
	v_cndmask_b32_e64 v23, v23, v156, s[42:43]
	v_cndmask_b32_e64 v22, v156, v22, s[42:43]
	v_cndmask_b32_e64 v145, v20, v22, s[44:45]
	v_cndmask_b32_e64 v147, v21, v23, s[44:45]
	s_nop 1
	v_mov_b32_dpp v146, v145 quad_perm:[2,3,0,1] row_mask:0xf bank_mask:0xf
	v_mov_b32_dpp v156, v147 quad_perm:[2,3,0,1] row_mask:0xf bank_mask:0xf
	v_cndmask_b32_e64 v22, v22, v146, s[44:45]
	v_cndmask_b32_e64 v20, v146, v20, s[44:45]
	v_cndmask_b32_e64 v23, v23, v156, s[44:45]
	v_cndmask_b32_e64 v21, v156, v21, s[44:45]
	v_cndmask_b32_e64 v145, v24, v25, s[42:43]
	v_cndmask_b32_e64 v147, v26, v27, s[42:43]
	s_nop 1
	v_mov_b32_dpp v146, v145 quad_perm:[1,0,3,2] row_mask:0xf bank_mask:0xf
	v_mov_b32_dpp v156, v147 quad_perm:[1,0,3,2] row_mask:0xf bank_mask:0xf
	v_cndmask_b32_e64 v25, v25, v146, s[42:43]
	v_cndmask_b32_e64 v24, v146, v24, s[42:43]
	v_cndmask_b32_e64 v27, v27, v156, s[42:43]
	v_cndmask_b32_e64 v26, v156, v26, s[42:43]
	v_cndmask_b32_e64 v145, v24, v26, s[44:45]
	v_cndmask_b32_e64 v147, v25, v27, s[44:45]
	s_nop 1
	v_mov_b32_dpp v146, v145 quad_perm:[2,3,0,1] row_mask:0xf bank_mask:0xf
	v_mov_b32_dpp v156, v147 quad_perm:[2,3,0,1] row_mask:0xf bank_mask:0xf
	v_cndmask_b32_e64 v26, v26, v146, s[44:45]
	v_cndmask_b32_e64 v24, v146, v24, s[44:45]
	v_cndmask_b32_e64 v27, v27, v156, s[44:45]
	v_cndmask_b32_e64 v25, v156, v25, s[44:45]
	v_cndmask_b32_e64 v145, v28, v29, s[42:43]
	v_cndmask_b32_e64 v147, v30, v31, s[42:43]
	s_nop 1
	v_mov_b32_dpp v146, v145 quad_perm:[1,0,3,2] row_mask:0xf bank_mask:0xf
	v_mov_b32_dpp v156, v147 quad_perm:[1,0,3,2] row_mask:0xf bank_mask:0xf
	v_cndmask_b32_e64 v29, v29, v146, s[42:43]
	v_cndmask_b32_e64 v28, v146, v28, s[42:43]
	v_cndmask_b32_e64 v31, v31, v156, s[42:43]
	v_cndmask_b32_e64 v30, v156, v30, s[42:43]
	v_cndmask_b32_e64 v145, v28, v30, s[44:45]
	v_cndmask_b32_e64 v147, v29, v31, s[44:45]
	s_nop 1
	v_mov_b32_dpp v146, v145 quad_perm:[2,3,0,1] row_mask:0xf bank_mask:0xf
	v_mov_b32_dpp v156, v147 quad_perm:[2,3,0,1] row_mask:0xf bank_mask:0xf
	v_cndmask_b32_e64 v30, v30, v146, s[44:45]
	v_cndmask_b32_e64 v28, v146, v28, s[44:45]
	v_cndmask_b32_e64 v31, v31, v156, s[44:45]
	v_cndmask_b32_e64 v29, v156, v29, s[44:45]
	v_cndmask_b32_e64 v145, v32, v33, s[42:43]
	v_cndmask_b32_e64 v147, v34, v35, s[42:43]
	s_nop 1
	v_mov_b32_dpp v146, v145 quad_perm:[1,0,3,2] row_mask:0xf bank_mask:0xf
	v_mov_b32_dpp v156, v147 quad_perm:[1,0,3,2] row_mask:0xf bank_mask:0xf
	v_cndmask_b32_e64 v33, v33, v146, s[42:43]
	v_cndmask_b32_e64 v32, v146, v32, s[42:43]
	v_cndmask_b32_e64 v35, v35, v156, s[42:43]
	v_cndmask_b32_e64 v34, v156, v34, s[42:43]
	v_cndmask_b32_e64 v145, v32, v34, s[44:45]
	v_cndmask_b32_e64 v147, v33, v35, s[44:45]
	s_nop 1
	v_mov_b32_dpp v146, v145 quad_perm:[2,3,0,1] row_mask:0xf bank_mask:0xf
	v_mov_b32_dpp v156, v147 quad_perm:[2,3,0,1] row_mask:0xf bank_mask:0xf
	v_cndmask_b32_e64 v34, v34, v146, s[44:45]
	v_cndmask_b32_e64 v32, v146, v32, s[44:45]
	v_cndmask_b32_e64 v35, v35, v156, s[44:45]
	v_cndmask_b32_e64 v33, v156, v33, s[44:45]
	v_add_u32_e32 v1, 0xd800, v142
	v_add_u32_e32 v2, 0xd800, v143
	v_add_u32_e32 v3, 0xd800, v144
	ds_read_b128 v[164:167], v3 offset:26624
	ds_read_b128 v[168:171], v3 offset:26688
	ds_read_b128 v[172:175], v3 offset:26752
	ds_read_b128 v[176:179], v3 offset:26816
	ds_read_b128 v[180:183], v3 offset:26880
	ds_read_b128 v[184:187], v3 offset:26944
	ds_read_b128 v[148:151], v3 offset:27008
	ds_read_b128 v[152:155], v3 offset:27072
	ds_read_b128 v[84:87], v2 offset:16384
	ds_read_b128 v[88:91], v1 offset:24576
	ds_read_b128 v[92:95], v1 offset:0
	ds_read_b128 v[96:99], v1 offset:1024
	ds_read_b128 v[100:103], v1 offset:2048
	ds_read_b128 v[104:107], v1 offset:3072
	v_cvt_pk_bf16_f32 v68, v4, v5
	v_cvt_pk_bf16_f32 v69, v6, v7
	v_cvt_pk_bf16_f32 v70, v8, v9
	v_cvt_pk_bf16_f32 v71, v10, v11
	v_cvt_pk_bf16_f32 v72, v12, v13
	v_cvt_pk_bf16_f32 v73, v14, v15
	v_cvt_pk_bf16_f32 v74, v16, v17
	v_cvt_pk_bf16_f32 v75, v18, v19
	v_cvt_pk_bf16_f32 v76, v20, v21
	v_cvt_pk_bf16_f32 v77, v22, v23
	v_cvt_pk_bf16_f32 v78, v24, v25
	v_cvt_pk_bf16_f32 v79, v26, v27
	v_cvt_pk_bf16_f32 v80, v28, v29
	v_cvt_pk_bf16_f32 v81, v30, v31
	v_cvt_pk_bf16_f32 v82, v32, v33
	v_cvt_pk_bf16_f32 v83, v34, v35
	s_waitcnt lgkmcnt(6)
; #define LAS __attribute__((address_space(3)))
; __device__ __forceinline__ unsigned pk2(float lo, float hi) { const f32x2_t_ v = {lo, hi}; return __builtin_bit_cast(unsigned, __builtin_convertvector(v, bf16x2_t_)); }
; __device__ __forceinline__ void hg_chunk(const LAS unsigned char* sl, f32x4 (&S)[8], float* Orow, int nvalid, int vs, int lane) {
;     ...
;     { const bf16x8 s0 = *(const LAS bf16x8*)(sl + 24576 + (lane << 4)), s1 = *(const LAS bf16x8*)(sl + 24576 + ((64 + lane) << 4));
;       o0 = __builtin_amdgcn_mfma_f32_16x16x32_bf16(s0, vfr, o0, 0, 0, 0); o1 = __builtin_amdgcn_mfma_f32_16x16x32_bf16(s1, vfr, o1, 0, 0, 0); }
; #pragma unroll
;     for (int m = 0; m < 4; ++m) {
;         v4u sw; sw.x = pk2(S[2 * m][0], S[2 * m][1]); sw.y = pk2(S[2 * m][2], S[2 * m][3]); sw.z = pk2(S[2 * m + 1][0], S[2 * m + 1][1]); sw.w = pk2(S[2 * m + 1][2], S[2 * m + 1][3]);
;         const bf16x8 sb = __builtin_bit_cast(bf16x8, sw);
;         const bf16x8 a0 = *(const LAS bf16x8*)(sl + ((m * 64 + lane) << 4)), a1 = *(const LAS bf16x8*)(sl + (((4 + m) * 64 + lane) << 4));
;         o0 = __builtin_amdgcn_mfma_f32_16x16x32_bf16(a0, sb, o0, 0, 0, 0); o1 = __builtin_amdgcn_mfma_f32_16x16x32_bf16(a1, sb, o1, 0, 0, 0);
;     }
; #pragma unroll
;     for (int i = 0; i < 4; ++i) { const int c0 = 4 * q + i;
;         if (c0 < nvalid) Orow[(size_t)c0 * DA + 16 * vs + r] = o0[i];
;         if (c0 + 16 < nvalid) Orow[(size_t)(c0 + 16) * DA + 16 * vs + r] = o1[i]; }
; #pragma unroll
;     for (int kb = 0; kb < 8; ++kb) { const f32x4 d = *(const LAS f32x4*)(sl + 26624 + ((16 * kb + 4 * q) << 2));
;         const bf16x8 ke = *(const LAS bf16x8*)(sl + 8192 + ((kb * 64 + lane) << 4));
;         S[kb] = __builtin_amdgcn_mfma_f32_16x16x32_bf16(ke, vfr, S[kb] * d, 0, 0, 0); }
; __device__ __forceinline__ void hg_seq(const Frame& F, unsigned char* ws, const float* s0, float* sout, float* Og, int seq, bool sample, int vs_base, int nvs) {
;     ...
;     if (active) {
; #pragma unroll
;     for (int kb = 0; kb < 8; ++kb)
; #pragma unroll
;         for (int i = 0; i < 4; ++i) sout[((size_t)seq * 128 + 16 * kb + 4 * q + i) * 128 + 16 * vs + r] = S[kb][i];
;     }
	v_pk_mul_f32 v[4:5], v[4:5], v[164:165]
	v_pk_mul_f32 v[6:7], v[6:7], v[166:167]
	v_pk_mul_f32 v[8:9], v[8:9], v[168:169]
	v_pk_mul_f32 v[10:11], v[10:11], v[170:171]
	v_pk_mul_f32 v[12:13], v[12:13], v[172:173]
	v_pk_mul_f32 v[14:15], v[14:15], v[174:175]
	v_pk_mul_f32 v[16:17], v[16:17], v[176:177]
	v_pk_mul_f32 v[18:19], v[18:19], v[178:179]
	v_pk_mul_f32 v[20:21], v[20:21], v[180:181]
	v_pk_mul_f32 v[22:23], v[22:23], v[182:183]
	v_pk_mul_f32 v[24:25], v[24:25], v[184:185]
	v_pk_mul_f32 v[26:27], v[26:27], v[186:187]
	v_pk_mul_f32 v[28:29], v[28:29], v[148:149]
	v_pk_mul_f32 v[30:31], v[30:31], v[150:151]
	v_pk_mul_f32 v[32:33], v[32:33], v[152:153]
	v_pk_mul_f32 v[34:35], v[34:35], v[154:155]
	ds_read_b128 v[108:111], v1 offset:8192
	ds_read_b128 v[112:115], v1 offset:9216
	ds_read_b128 v[116:119], v1 offset:10240
	ds_read_b128 v[120:123], v1 offset:11264
	ds_read_b128 v[124:127], v1 offset:12288
	ds_read_b128 v[128:131], v1 offset:13312
	ds_read_b128 v[132:135], v1 offset:14336
	ds_read_b128 v[136:139], v1 offset:15360
	s_waitcnt lgkmcnt(12)
	v_mfma_f32_16x16x32_bf16 v[196:199], v[88:91], v[84:87], 0
	s_waitcnt lgkmcnt(11)
	v_mfma_f32_16x16x32_bf16 v[196:199], v[92:95], v[68:71], v[196:199]
	s_waitcnt lgkmcnt(10)
	v_mfma_f32_16x16x32_bf16 v[196:199], v[96:99], v[72:75], v[196:199]
	s_waitcnt lgkmcnt(9)
	v_mfma_f32_16x16x32_bf16 v[196:199], v[100:103], v[76:79], v[196:199]
	s_waitcnt lgkmcnt(8)
	v_mfma_f32_16x16x32_bf16 v[196:199], v[104:107], v[80:83], v[196:199]
	s_waitcnt lgkmcnt(7)
	v_mfma_f32_16x16x32_bf16 v[4:7], v[108:111], v[84:87], v[4:7]
	s_waitcnt lgkmcnt(6)
	v_mfma_f32_16x16x32_bf16 v[8:11], v[112:115], v[84:87], v[8:11]
	s_waitcnt lgkmcnt(5)
	v_mfma_f32_16x16x32_bf16 v[12:15], v[116:119], v[84:87], v[12:15]
	s_waitcnt lgkmcnt(4)
	v_mfma_f32_16x16x32_bf16 v[16:19], v[120:123], v[84:87], v[16:19]
	s_waitcnt lgkmcnt(3)
	v_mfma_f32_16x16x32_bf16 v[20:23], v[124:127], v[84:87], v[20:23]
	s_waitcnt lgkmcnt(2)
	v_mfma_f32_16x16x32_bf16 v[24:27], v[128:131], v[84:87], v[24:27]
	s_waitcnt lgkmcnt(1)
	v_mfma_f32_16x16x32_bf16 v[28:31], v[132:135], v[84:87], v[28:31]
	s_waitcnt lgkmcnt(0)
	v_mfma_f32_16x16x32_bf16 v[32:35], v[136:139], v[84:87], v[32:35]
	s_mov_b32 exec_hi, 0
	global_store_dword v208, v196, s[12:13]
	global_store_dword v208, v197, s[12:13] offset:2048
	global_store_dword v209, v198, s[12:13]
	global_store_dword v209, v199, s[12:13] offset:2048
	s_mov_b64 exec, -1
	s_add_u32 s12, s12, 0x80000
	s_addc_u32 s13, s13, 0
	s_nop 7
	v_cndmask_b32_e64 v145, v4, v5, s[42:43]
	v_cndmask_b32_e64 v147, v6, v7, s[42:43]
	s_nop 1
	v_mov_b32_dpp v146, v145 quad_perm:[1,0,3,2] row_mask:0xf bank_mask:0xf
	v_mov_b32_dpp v156, v147 quad_perm:[1,0,3,2] row_mask:0xf bank_mask:0xf
	v_cndmask_b32_e64 v5, v5, v146, s[42:43]
	v_cndmask_b32_e64 v4, v146, v4, s[42:43]
	v_cndmask_b32_e64 v7, v7, v156, s[42:43]
	v_cndmask_b32_e64 v6, v156, v6, s[42:43]
	v_cndmask_b32_e64 v145, v4, v6, s[44:45]
	v_cndmask_b32_e64 v147, v5, v7, s[44:45]
	s_nop 1
	v_mov_b32_dpp v146, v145 quad_perm:[2,3,0,1] row_mask:0xf bank_mask:0xf
	v_mov_b32_dpp v156, v147 quad_perm:[2,3,0,1] row_mask:0xf bank_mask:0xf
	v_cndmask_b32_e64 v6, v6, v146, s[44:45]
	v_cndmask_b32_e64 v4, v146, v4, s[44:45]
	v_cndmask_b32_e64 v7, v7, v156, s[44:45]
	v_cndmask_b32_e64 v5, v156, v5, s[44:45]
	v_cndmask_b32_e64 v145, v8, v9, s[42:43]
	v_cndmask_b32_e64 v147, v10, v11, s[42:43]
	s_nop 1
	v_mov_b32_dpp v146, v145 quad_perm:[1,0,3,2] row_mask:0xf bank_mask:0xf
	v_mov_b32_dpp v156, v147 quad_perm:[1,0,3,2] row_mask:0xf bank_mask:0xf
	v_cndmask_b32_e64 v9, v9, v146, s[42:43]
	v_cndmask_b32_e64 v8, v146, v8, s[42:43]
	v_cndmask_b32_e64 v11, v11, v156, s[42:43]
	v_cndmask_b32_e64 v10, v156, v10, s[42:43]
	v_cndmask_b32_e64 v145, v8, v10, s[44:45]
	v_cndmask_b32_e64 v147, v9, v11, s[44:45]
	s_nop 1
	v_mov_b32_dpp v146, v145 quad_perm:[2,3,0,1] row_mask:0xf bank_mask:0xf
	v_mov_b32_dpp v156, v147 quad_perm:[2,3,0,1] row_mask:0xf bank_mask:0xf
	v_cndmask_b32_e64 v10, v10, v146, s[44:45]
	v_cndmask_b32_e64 v8, v146, v8, s[44:45]
	v_cndmask_b32_e64 v11, v11, v156, s[44:45]
	v_cndmask_b32_e64 v9, v156, v9, s[44:45]
	v_cndmask_b32_e64 v145, v12, v13, s[42:43]
	v_cndmask_b32_e64 v147, v14, v15, s[42:43]
	s_nop 1
	v_mov_b32_dpp v146, v145 quad_perm:[1,0,3,2] row_mask:0xf bank_mask:0xf
	v_mov_b32_dpp v156, v147 quad_perm:[1,0,3,2] row_mask:0xf bank_mask:0xf
	v_cndmask_b32_e64 v13, v13, v146, s[42:43]
	v_cndmask_b32_e64 v12, v146, v12, s[42:43]
	v_cndmask_b32_e64 v15, v15, v156, s[42:43]
	v_cndmask_b32_e64 v14, v156, v14, s[42:43]
	v_cndmask_b32_e64 v145, v12, v14, s[44:45]
	v_cndmask_b32_e64 v147, v13, v15, s[44:45]
	s_nop 1
	v_mov_b32_dpp v146, v145 quad_perm:[2,3,0,1] row_mask:0xf bank_mask:0xf
	v_mov_b32_dpp v156, v147 quad_perm:[2,3,0,1] row_mask:0xf bank_mask:0xf
	v_cndmask_b32_e64 v14, v14, v146, s[44:45]
	v_cndmask_b32_e64 v12, v146, v12, s[44:45]
	v_cndmask_b32_e64 v15, v15, v156, s[44:45]
	v_cndmask_b32_e64 v13, v156, v13, s[44:45]
	v_cndmask_b32_e64 v145, v16, v17, s[42:43]
	v_cndmask_b32_e64 v147, v18, v19, s[42:43]
	s_nop 1
	v_mov_b32_dpp v146, v145 quad_perm:[1,0,3,2] row_mask:0xf bank_mask:0xf
	v_mov_b32_dpp v156, v147 quad_perm:[1,0,3,2] row_mask:0xf bank_mask:0xf
	v_cndmask_b32_e64 v17, v17, v146, s[42:43]
	v_cndmask_b32_e64 v16, v146, v16, s[42:43]
	v_cndmask_b32_e64 v19, v19, v156, s[42:43]
	v_cndmask_b32_e64 v18, v156, v18, s[42:43]
	v_cndmask_b32_e64 v145, v16, v18, s[44:45]
	v_cndmask_b32_e64 v147, v17, v19, s[44:45]
	s_nop 1
	v_mov_b32_dpp v146, v145 quad_perm:[2,3,0,1] row_mask:0xf bank_mask:0xf
	v_mov_b32_dpp v156, v147 quad_perm:[2,3,0,1] row_mask:0xf bank_mask:0xf
; __device__ __forceinline__ void hg_seq(const Frame& F, unsigned char* ws, const float* s0, float* sout, float* Og, int seq, bool sample, int vs_base, int nvs) {
;     ...
;     if (sample && active) {
; #pragma unroll
;         for (int kb = 0; kb < 8; ++kb)
; #pragma unroll
;             for (int i = 0; i < 4; ++i) S[kb][i] = s0[((size_t)seq * 128 + 16 * kb + 4 * q + i) * 128 + 16 * vs + r];
;     } else {
;     ...
;     if (active) {
; #pragma unroll
;     for (int kb = 0; kb < 8; ++kb)
; #pragma unroll
;         for (int i = 0; i < 4; ++i) sout[((size_t)seq * 128 + 16 * kb + 4 * q + i) * 128 + 16 * vs + r] = S[kb][i];
;     }
	v_cndmask_b32_e64 v18, v18, v146, s[44:45]
	v_cndmask_b32_e64 v16, v146, v16, s[44:45]
	v_cndmask_b32_e64 v19, v19, v156, s[44:45]
	v_cndmask_b32_e64 v17, v156, v17, s[44:45]
	v_cndmask_b32_e64 v145, v20, v21, s[42:43]
	v_cndmask_b32_e64 v147, v22, v23, s[42:43]
	s_nop 1
	v_mov_b32_dpp v146, v145 quad_perm:[1,0,3,2] row_mask:0xf bank_mask:0xf
	v_mov_b32_dpp v156, v147 quad_perm:[1,0,3,2] row_mask:0xf bank_mask:0xf
	v_cndmask_b32_e64 v21, v21, v146, s[42:43]
	v_cndmask_b32_e64 v20, v146, v20, s[42:43]
	v_cndmask_b32_e64 v23, v23, v156, s[42:43]
	v_cndmask_b32_e64 v22, v156, v22, s[42:43]
	v_cndmask_b32_e64 v145, v20, v22, s[44:45]
	v_cndmask_b32_e64 v147, v21, v23, s[44:45]
	s_nop 1
	v_mov_b32_dpp v146, v145 quad_perm:[2,3,0,1] row_mask:0xf bank_mask:0xf
	v_mov_b32_dpp v156, v147 quad_perm:[2,3,0,1] row_mask:0xf bank_mask:0xf
	v_cndmask_b32_e64 v22, v22, v146, s[44:45]
	v_cndmask_b32_e64 v20, v146, v20, s[44:45]
	v_cndmask_b32_e64 v23, v23, v156, s[44:45]
	v_cndmask_b32_e64 v21, v156, v21, s[44:45]
	v_cndmask_b32_e64 v145, v24, v25, s[42:43]
	v_cndmask_b32_e64 v147, v26, v27, s[42:43]
	s_nop 1
	v_mov_b32_dpp v146, v145 quad_perm:[1,0,3,2] row_mask:0xf bank_mask:0xf
	v_mov_b32_dpp v156, v147 quad_perm:[1,0,3,2] row_mask:0xf bank_mask:0xf
	v_cndmask_b32_e64 v25, v25, v146, s[42:43]
	v_cndmask_b32_e64 v24, v146, v24, s[42:43]
	v_cndmask_b32_e64 v27, v27, v156, s[42:43]
	v_cndmask_b32_e64 v26, v156, v26, s[42:43]
	v_cndmask_b32_e64 v145, v24, v26, s[44:45]
	v_cndmask_b32_e64 v147, v25, v27, s[44:45]
	s_nop 1
	v_mov_b32_dpp v146, v145 quad_perm:[2,3,0,1] row_mask:0xf bank_mask:0xf
	v_mov_b32_dpp v156, v147 quad_perm:[2,3,0,1] row_mask:0xf bank_mask:0xf
	v_cndmask_b32_e64 v26, v26, v146, s[44:45]
	v_cndmask_b32_e64 v24, v146, v24, s[44:45]
	v_cndmask_b32_e64 v27, v27, v156, s[44:45]
	v_cndmask_b32_e64 v25, v156, v25, s[44:45]
	v_cndmask_b32_e64 v145, v28, v29, s[42:43]
	v_cndmask_b32_e64 v147, v30, v31, s[42:43]
	s_nop 1
	v_mov_b32_dpp v146, v145 quad_perm:[1,0,3,2] row_mask:0xf bank_mask:0xf
	v_mov_b32_dpp v156, v147 quad_perm:[1,0,3,2] row_mask:0xf bank_mask:0xf
	v_cndmask_b32_e64 v29, v29, v146, s[42:43]
	v_cndmask_b32_e64 v28, v146, v28, s[42:43]
	v_cndmask_b32_e64 v31, v31, v156, s[42:43]
	v_cndmask_b32_e64 v30, v156, v30, s[42:43]
	v_cndmask_b32_e64 v145, v28, v30, s[44:45]
	v_cndmask_b32_e64 v147, v29, v31, s[44:45]
	s_nop 1
	v_mov_b32_dpp v146, v145 quad_perm:[2,3,0,1] row_mask:0xf bank_mask:0xf
	v_mov_b32_dpp v156, v147 quad_perm:[2,3,0,1] row_mask:0xf bank_mask:0xf
	v_cndmask_b32_e64 v30, v30, v146, s[44:45]
	v_cndmask_b32_e64 v28, v146, v28, s[44:45]
	v_cndmask_b32_e64 v31, v31, v156, s[44:45]
	v_cndmask_b32_e64 v29, v156, v29, s[44:45]
	v_cndmask_b32_e64 v145, v32, v33, s[42:43]
	v_cndmask_b32_e64 v147, v34, v35, s[42:43]
	s_nop 1
	v_mov_b32_dpp v146, v145 quad_perm:[1,0,3,2] row_mask:0xf bank_mask:0xf
	v_mov_b32_dpp v156, v147 quad_perm:[1,0,3,2] row_mask:0xf bank_mask:0xf
	v_cndmask_b32_e64 v33, v33, v146, s[42:43]
	v_cndmask_b32_e64 v32, v146, v32, s[42:43]
	v_cndmask_b32_e64 v35, v35, v156, s[42:43]
	v_cndmask_b32_e64 v34, v156, v34, s[42:43]
	v_cndmask_b32_e64 v145, v32, v34, s[44:45]
	v_cndmask_b32_e64 v147, v33, v35, s[44:45]
	s_nop 1
	v_mov_b32_dpp v146, v145 quad_perm:[2,3,0,1] row_mask:0xf bank_mask:0xf
	v_mov_b32_dpp v156, v147 quad_perm:[2,3,0,1] row_mask:0xf bank_mask:0xf
	v_cndmask_b32_e64 v34, v34, v146, s[44:45]
	v_cndmask_b32_e64 v32, v146, v32, s[44:45]
	v_cndmask_b32_e64 v35, v35, v156, s[44:45]
	v_cndmask_b32_e64 v33, v156, v33, s[44:45]
	global_store_dwordx4 v200, v[4:7], s[10:11]
	global_store_dwordx4 v201, v[8:11], s[10:11]
	global_store_dwordx4 v202, v[12:15], s[10:11]
	global_store_dwordx4 v203, v[16:19], s[10:11]
	global_store_dwordx4 v204, v[20:23], s[10:11]
	global_store_dwordx4 v205, v[24:27], s[10:11]
	global_store_dwordx4 v206, v[28:31], s[10:11]
	global_store_dwordx4 v207, v[32:35], s[10:11]
	s_add_u32 s10, s10, s34
	s_addc_u32 s11, s11, 0
	s_waitcnt vmcnt(12)
	v_cndmask_b32_e64 v145, v36, v37, s[42:43]
	v_cndmask_b32_e64 v147, v38, v39, s[42:43]
	s_nop 1
	v_mov_b32_dpp v146, v145 quad_perm:[1,0,3,2] row_mask:0xf bank_mask:0xf
	v_mov_b32_dpp v156, v147 quad_perm:[1,0,3,2] row_mask:0xf bank_mask:0xf
	v_cndmask_b32_e64 v37, v37, v146, s[42:43]
	v_cndmask_b32_e64 v36, v146, v36, s[42:43]
	v_cndmask_b32_e64 v39, v39, v156, s[42:43]
	v_cndmask_b32_e64 v38, v156, v38, s[42:43]
	v_cndmask_b32_e64 v145, v36, v38, s[44:45]
	v_cndmask_b32_e64 v147, v37, v39, s[44:45]
	s_nop 1
	v_mov_b32_dpp v146, v145 quad_perm:[2,3,0,1] row_mask:0xf bank_mask:0xf
	v_mov_b32_dpp v156, v147 quad_perm:[2,3,0,1] row_mask:0xf bank_mask:0xf
	v_cndmask_b32_e64 v38, v38, v146, s[44:45]
	v_cndmask_b32_e64 v36, v146, v36, s[44:45]
	v_cndmask_b32_e64 v39, v39, v156, s[44:45]
	v_cndmask_b32_e64 v37, v156, v37, s[44:45]
	v_cndmask_b32_e64 v145, v40, v41, s[42:43]
	v_cndmask_b32_e64 v147, v42, v43, s[42:43]
	s_nop 1
	v_mov_b32_dpp v146, v145 quad_perm:[1,0,3,2] row_mask:0xf bank_mask:0xf
	v_mov_b32_dpp v156, v147 quad_perm:[1,0,3,2] row_mask:0xf bank_mask:0xf
	v_cndmask_b32_e64 v41, v41, v146, s[42:43]
	v_cndmask_b32_e64 v40, v146, v40, s[42:43]
	v_cndmask_b32_e64 v43, v43, v156, s[42:43]
	v_cndmask_b32_e64 v42, v156, v42, s[42:43]
	v_cndmask_b32_e64 v145, v40, v42, s[44:45]
	v_cndmask_b32_e64 v147, v41, v43, s[44:45]
	s_nop 1
	v_mov_b32_dpp v146, v145 quad_perm:[2,3,0,1] row_mask:0xf bank_mask:0xf
	v_mov_b32_dpp v156, v147 quad_perm:[2,3,0,1] row_mask:0xf bank_mask:0xf
	v_cndmask_b32_e64 v42, v42, v146, s[44:45]
	v_cndmask_b32_e64 v40, v146, v40, s[44:45]
	v_cndmask_b32_e64 v43, v43, v156, s[44:45]
	v_cndmask_b32_e64 v41, v156, v41, s[44:45]
; #define LAS __attribute__((address_space(3)))
; __device__ __forceinline__ unsigned pk2(float lo, float hi) { const f32x2_t_ v = {lo, hi}; return __builtin_bit_cast(unsigned, __builtin_convertvector(v, bf16x2_t_)); }
; __device__ __forceinline__ void hg_chunk(const LAS unsigned char* sl, f32x4 (&S)[8], float* Orow, int nvalid, int vs, int lane) {
;     const int r = lane & 15, q = lane >> 4;
;     const bf16x8 vfr = *(const LAS bf16x8*)(sl + 16384 + ((vs * 64 + lane) << 4));
;     f32x4 o0 = {0.f, 0.f, 0.f, 0.f}, o1 = {0.f, 0.f, 0.f, 0.f};
;     { const bf16x8 s0 = *(const LAS bf16x8*)(sl + 24576 + (lane << 4)), s1 = *(const LAS bf16x8*)(sl + 24576 + ((64 + lane) << 4));
;       o0 = __builtin_amdgcn_mfma_f32_16x16x32_bf16(s0, vfr, o0, 0, 0, 0); o1 = __builtin_amdgcn_mfma_f32_16x16x32_bf16(s1, vfr, o1, 0, 0, 0); }
; #pragma unroll
;     for (int m = 0; m < 4; ++m) {
;         v4u sw; sw.x = pk2(S[2 * m][0], S[2 * m][1]); sw.y = pk2(S[2 * m][2], S[2 * m][3]); sw.z = pk2(S[2 * m + 1][0], S[2 * m + 1][1]); sw.w = pk2(S[2 * m + 1][2], S[2 * m + 1][3]);
;         const bf16x8 sb = __builtin_bit_cast(bf16x8, sw);
;         const bf16x8 a0 = *(const LAS bf16x8*)(sl + ((m * 64 + lane) << 4)), a1 = *(const LAS bf16x8*)(sl + (((4 + m) * 64 + lane) << 4));
; __device__ __forceinline__ void hg_seq(const Frame& F, unsigned char* ws, const float* s0, float* sout, float* Og, int seq, bool sample, int vs_base, int nvs) {
;     ...
;     if (sample && active) {
; #pragma unroll
;         for (int kb = 0; kb < 8; ++kb)
; #pragma unroll
;             for (int i = 0; i < 4; ++i) S[kb][i] = s0[((size_t)seq * 128 + 16 * kb + 4 * q + i) * 128 + 16 * vs + r];
;     } else {
	v_cndmask_b32_e64 v145, v44, v45, s[42:43]
	v_cndmask_b32_e64 v147, v46, v47, s[42:43]
	s_nop 1
	v_mov_b32_dpp v146, v145 quad_perm:[1,0,3,2] row_mask:0xf bank_mask:0xf
	v_mov_b32_dpp v156, v147 quad_perm:[1,0,3,2] row_mask:0xf bank_mask:0xf
	v_cndmask_b32_e64 v45, v45, v146, s[42:43]
	v_cndmask_b32_e64 v44, v146, v44, s[42:43]
	v_cndmask_b32_e64 v47, v47, v156, s[42:43]
	v_cndmask_b32_e64 v46, v156, v46, s[42:43]
	v_cndmask_b32_e64 v145, v44, v46, s[44:45]
	v_cndmask_b32_e64 v147, v45, v47, s[44:45]
	s_nop 1
	v_mov_b32_dpp v146, v145 quad_perm:[2,3,0,1] row_mask:0xf bank_mask:0xf
	v_mov_b32_dpp v156, v147 quad_perm:[2,3,0,1] row_mask:0xf bank_mask:0xf
	v_cndmask_b32_e64 v46, v46, v146, s[44:45]
	v_cndmask_b32_e64 v44, v146, v44, s[44:45]
	v_cndmask_b32_e64 v47, v47, v156, s[44:45]
	v_cndmask_b32_e64 v45, v156, v45, s[44:45]
	v_cndmask_b32_e64 v145, v48, v49, s[42:43]
	v_cndmask_b32_e64 v147, v50, v51, s[42:43]
	s_nop 1
	v_mov_b32_dpp v146, v145 quad_perm:[1,0,3,2] row_mask:0xf bank_mask:0xf
	v_mov_b32_dpp v156, v147 quad_perm:[1,0,3,2] row_mask:0xf bank_mask:0xf
	v_cndmask_b32_e64 v49, v49, v146, s[42:43]
	v_cndmask_b32_e64 v48, v146, v48, s[42:43]
	v_cndmask_b32_e64 v51, v51, v156, s[42:43]
	v_cndmask_b32_e64 v50, v156, v50, s[42:43]
	v_cndmask_b32_e64 v145, v48, v50, s[44:45]
	v_cndmask_b32_e64 v147, v49, v51, s[44:45]
	s_nop 1
	v_mov_b32_dpp v146, v145 quad_perm:[2,3,0,1] row_mask:0xf bank_mask:0xf
	v_mov_b32_dpp v156, v147 quad_perm:[2,3,0,1] row_mask:0xf bank_mask:0xf
	v_cndmask_b32_e64 v50, v50, v146, s[44:45]
	v_cndmask_b32_e64 v48, v146, v48, s[44:45]
	v_cndmask_b32_e64 v51, v51, v156, s[44:45]
	v_cndmask_b32_e64 v49, v156, v49, s[44:45]
	v_cndmask_b32_e64 v145, v52, v53, s[42:43]
	v_cndmask_b32_e64 v147, v54, v55, s[42:43]
	s_nop 1
	v_mov_b32_dpp v146, v145 quad_perm:[1,0,3,2] row_mask:0xf bank_mask:0xf
	v_mov_b32_dpp v156, v147 quad_perm:[1,0,3,2] row_mask:0xf bank_mask:0xf
	v_cndmask_b32_e64 v53, v53, v146, s[42:43]
	v_cndmask_b32_e64 v52, v146, v52, s[42:43]
	v_cndmask_b32_e64 v55, v55, v156, s[42:43]
	v_cndmask_b32_e64 v54, v156, v54, s[42:43]
	v_cndmask_b32_e64 v145, v52, v54, s[44:45]
	v_cndmask_b32_e64 v147, v53, v55, s[44:45]
	s_nop 1
	v_mov_b32_dpp v146, v145 quad_perm:[2,3,0,1] row_mask:0xf bank_mask:0xf
	v_mov_b32_dpp v156, v147 quad_perm:[2,3,0,1] row_mask:0xf bank_mask:0xf
	v_cndmask_b32_e64 v54, v54, v146, s[44:45]
	v_cndmask_b32_e64 v52, v146, v52, s[44:45]
	v_cndmask_b32_e64 v55, v55, v156, s[44:45]
	v_cndmask_b32_e64 v53, v156, v53, s[44:45]
	v_cndmask_b32_e64 v145, v56, v57, s[42:43]
	v_cndmask_b32_e64 v147, v58, v59, s[42:43]
	s_nop 1
	v_mov_b32_dpp v146, v145 quad_perm:[1,0,3,2] row_mask:0xf bank_mask:0xf
	v_mov_b32_dpp v156, v147 quad_perm:[1,0,3,2] row_mask:0xf bank_mask:0xf
	v_cndmask_b32_e64 v57, v57, v146, s[42:43]
	v_cndmask_b32_e64 v56, v146, v56, s[42:43]
	v_cndmask_b32_e64 v59, v59, v156, s[42:43]
	v_cndmask_b32_e64 v58, v156, v58, s[42:43]
	v_cndmask_b32_e64 v145, v56, v58, s[44:45]
	v_cndmask_b32_e64 v147, v57, v59, s[44:45]
	s_nop 1
	v_mov_b32_dpp v146, v145 quad_perm:[2,3,0,1] row_mask:0xf bank_mask:0xf
	v_mov_b32_dpp v156, v147 quad_perm:[2,3,0,1] row_mask:0xf bank_mask:0xf
	v_cndmask_b32_e64 v58, v58, v146, s[44:45]
	v_cndmask_b32_e64 v56, v146, v56, s[44:45]
	v_cndmask_b32_e64 v59, v59, v156, s[44:45]
	v_cndmask_b32_e64 v57, v156, v57, s[44:45]
	v_cndmask_b32_e64 v145, v60, v61, s[42:43]
	v_cndmask_b32_e64 v147, v62, v63, s[42:43]
	s_nop 1
	v_mov_b32_dpp v146, v145 quad_perm:[1,0,3,2] row_mask:0xf bank_mask:0xf
	v_mov_b32_dpp v156, v147 quad_perm:[1,0,3,2] row_mask:0xf bank_mask:0xf
	v_cndmask_b32_e64 v61, v61, v146, s[42:43]
	v_cndmask_b32_e64 v60, v146, v60, s[42:43]
	v_cndmask_b32_e64 v63, v63, v156, s[42:43]
	v_cndmask_b32_e64 v62, v156, v62, s[42:43]
	v_cndmask_b32_e64 v145, v60, v62, s[44:45]
	v_cndmask_b32_e64 v147, v61, v63, s[44:45]
	s_nop 1
	v_mov_b32_dpp v146, v145 quad_perm:[2,3,0,1] row_mask:0xf bank_mask:0xf
	v_mov_b32_dpp v156, v147 quad_perm:[2,3,0,1] row_mask:0xf bank_mask:0xf
	v_cndmask_b32_e64 v62, v62, v146, s[44:45]
	v_cndmask_b32_e64 v60, v146, v60, s[44:45]
	v_cndmask_b32_e64 v63, v63, v156, s[44:45]
	v_cndmask_b32_e64 v61, v156, v61, s[44:45]
	v_cndmask_b32_e64 v145, v64, v65, s[42:43]
	v_cndmask_b32_e64 v147, v66, v67, s[42:43]
	s_nop 1
	v_mov_b32_dpp v146, v145 quad_perm:[1,0,3,2] row_mask:0xf bank_mask:0xf
	v_mov_b32_dpp v156, v147 quad_perm:[1,0,3,2] row_mask:0xf bank_mask:0xf
	v_cndmask_b32_e64 v65, v65, v146, s[42:43]
	v_cndmask_b32_e64 v64, v146, v64, s[42:43]
	v_cndmask_b32_e64 v67, v67, v156, s[42:43]
	v_cndmask_b32_e64 v66, v156, v66, s[42:43]
	v_cndmask_b32_e64 v145, v64, v66, s[44:45]
	v_cndmask_b32_e64 v147, v65, v67, s[44:45]
	s_nop 1
	v_mov_b32_dpp v146, v145 quad_perm:[2,3,0,1] row_mask:0xf bank_mask:0xf
	v_mov_b32_dpp v156, v147 quad_perm:[2,3,0,1] row_mask:0xf bank_mask:0xf
	v_cndmask_b32_e64 v66, v66, v146, s[44:45]
	v_cndmask_b32_e64 v64, v146, v64, s[44:45]
	v_cndmask_b32_e64 v67, v67, v156, s[44:45]
	v_cndmask_b32_e64 v65, v156, v65, s[44:45]
	v_add_u32_e32 v1, 0x14400, v142
	v_add_u32_e32 v2, 0x14400, v143
	v_add_u32_e32 v3, 0x14400, v144
	ds_read_b128 v[164:167], v3 offset:26624
	ds_read_b128 v[168:171], v3 offset:26688
	ds_read_b128 v[172:175], v3 offset:26752
	ds_read_b128 v[176:179], v3 offset:26816
	ds_read_b128 v[180:183], v3 offset:26880
	ds_read_b128 v[184:187], v3 offset:26944
	ds_read_b128 v[148:151], v3 offset:27008
	ds_read_b128 v[152:155], v3 offset:27072
	ds_read_b128 v[84:87], v2 offset:16384
	ds_read_b128 v[88:91], v1 offset:24576
	ds_read_b128 v[92:95], v1 offset:0
	ds_read_b128 v[96:99], v1 offset:1024
	ds_read_b128 v[100:103], v1 offset:2048
	ds_read_b128 v[104:107], v1 offset:3072
	v_cvt_pk_bf16_f32 v68, v36, v37
	v_cvt_pk_bf16_f32 v69, v38, v39
	v_cvt_pk_bf16_f32 v70, v40, v41
	v_cvt_pk_bf16_f32 v71, v42, v43
	v_cvt_pk_bf16_f32 v72, v44, v45
	v_cvt_pk_bf16_f32 v73, v46, v47
	v_cvt_pk_bf16_f32 v74, v48, v49
	v_cvt_pk_bf16_f32 v75, v50, v51
	v_cvt_pk_bf16_f32 v76, v52, v53
	v_cvt_pk_bf16_f32 v77, v54, v55
	v_cvt_pk_bf16_f32 v78, v56, v57
	v_cvt_pk_bf16_f32 v79, v58, v59
	v_cvt_pk_bf16_f32 v80, v60, v61
	v_cvt_pk_bf16_f32 v81, v62, v63
	v_cvt_pk_bf16_f32 v82, v64, v65
	v_cvt_pk_bf16_f32 v83, v66, v67
	s_waitcnt lgkmcnt(6)
; #define LAS __attribute__((address_space(3)))
; __device__ __forceinline__ unsigned pk2(float lo, float hi) { const f32x2_t_ v = {lo, hi}; return __builtin_bit_cast(unsigned, __builtin_convertvector(v, bf16x2_t_)); }
; __device__ __forceinline__ void hg_chunk(const LAS unsigned char* sl, f32x4 (&S)[8], float* Orow, int nvalid, int vs, int lane) {
;     ...
;     { const bf16x8 s0 = *(const LAS bf16x8*)(sl + 24576 + (lane << 4)), s1 = *(const LAS bf16x8*)(sl + 24576 + ((64 + lane) << 4));
;       o0 = __builtin_amdgcn_mfma_f32_16x16x32_bf16(s0, vfr, o0, 0, 0, 0); o1 = __builtin_amdgcn_mfma_f32_16x16x32_bf16(s1, vfr, o1, 0, 0, 0); }
; #pragma unroll
;     for (int m = 0; m < 4; ++m) {
;         v4u sw; sw.x = pk2(S[2 * m][0], S[2 * m][1]); sw.y = pk2(S[2 * m][2], S[2 * m][3]); sw.z = pk2(S[2 * m + 1][0], S[2 * m + 1][1]); sw.w = pk2(S[2 * m + 1][2], S[2 * m + 1][3]);
;         const bf16x8 sb = __builtin_bit_cast(bf16x8, sw);
;         const bf16x8 a0 = *(const LAS bf16x8*)(sl + ((m * 64 + lane) << 4)), a1 = *(const LAS bf16x8*)(sl + (((4 + m) * 64 + lane) << 4));
;         o0 = __builtin_amdgcn_mfma_f32_16x16x32_bf16(a0, sb, o0, 0, 0, 0); o1 = __builtin_amdgcn_mfma_f32_16x16x32_bf16(a1, sb, o1, 0, 0, 0);
;     }
; #pragma unroll
;     for (int i = 0; i < 4; ++i) { const int c0 = 4 * q + i;
;         if (c0 < nvalid) Orow[(size_t)c0 * DA + 16 * vs + r] = o0[i];
;         if (c0 + 16 < nvalid) Orow[(size_t)(c0 + 16) * DA + 16 * vs + r] = o1[i]; }
; #pragma unroll
;     for (int kb = 0; kb < 8; ++kb) { const f32x4 d = *(const LAS f32x4*)(sl + 26624 + ((16 * kb + 4 * q) << 2));
;         const bf16x8 ke = *(const LAS bf16x8*)(sl + 8192 + ((kb * 64 + lane) << 4));
;         S[kb] = __builtin_amdgcn_mfma_f32_16x16x32_bf16(ke, vfr, S[kb] * d, 0, 0, 0); }
; __device__ __forceinline__ void hg_seq(const Frame& F, unsigned char* ws, const float* s0, float* sout, float* Og, int seq, bool sample, int vs_base, int nvs) {
;     ...
;     if (active) {
; #pragma unroll
;     for (int kb = 0; kb < 8; ++kb)
; #pragma unroll
;         for (int i = 0; i < 4; ++i) sout[((size_t)seq * 128 + 16 * kb + 4 * q + i) * 128 + 16 * vs + r] = S[kb][i];
;     }
	v_pk_mul_f32 v[36:37], v[36:37], v[164:165]
	v_pk_mul_f32 v[38:39], v[38:39], v[166:167]
	v_pk_mul_f32 v[40:41], v[40:41], v[168:169]
	v_pk_mul_f32 v[42:43], v[42:43], v[170:171]
	v_pk_mul_f32 v[44:45], v[44:45], v[172:173]
	v_pk_mul_f32 v[46:47], v[46:47], v[174:175]
	v_pk_mul_f32 v[48:49], v[48:49], v[176:177]
	v_pk_mul_f32 v[50:51], v[50:51], v[178:179]
	v_pk_mul_f32 v[52:53], v[52:53], v[180:181]
	v_pk_mul_f32 v[54:55], v[54:55], v[182:183]
	v_pk_mul_f32 v[56:57], v[56:57], v[184:185]
	v_pk_mul_f32 v[58:59], v[58:59], v[186:187]
	v_pk_mul_f32 v[60:61], v[60:61], v[148:149]
	v_pk_mul_f32 v[62:63], v[62:63], v[150:151]
	v_pk_mul_f32 v[64:65], v[64:65], v[152:153]
	v_pk_mul_f32 v[66:67], v[66:67], v[154:155]
	ds_read_b128 v[108:111], v1 offset:8192
	ds_read_b128 v[112:115], v1 offset:9216
	ds_read_b128 v[116:119], v1 offset:10240
	ds_read_b128 v[120:123], v1 offset:11264
	ds_read_b128 v[124:127], v1 offset:12288
	ds_read_b128 v[128:131], v1 offset:13312
	ds_read_b128 v[132:135], v1 offset:14336
	ds_read_b128 v[136:139], v1 offset:15360
	s_waitcnt lgkmcnt(12)
	v_mfma_f32_16x16x32_bf16 v[196:199], v[88:91], v[84:87], 0
	s_waitcnt lgkmcnt(11)
	v_mfma_f32_16x16x32_bf16 v[196:199], v[92:95], v[68:71], v[196:199]
	s_waitcnt lgkmcnt(10)
	v_mfma_f32_16x16x32_bf16 v[196:199], v[96:99], v[72:75], v[196:199]
	s_waitcnt lgkmcnt(9)
	v_mfma_f32_16x16x32_bf16 v[196:199], v[100:103], v[76:79], v[196:199]
	s_waitcnt lgkmcnt(8)
	v_mfma_f32_16x16x32_bf16 v[196:199], v[104:107], v[80:83], v[196:199]
	s_waitcnt lgkmcnt(7)
	v_mfma_f32_16x16x32_bf16 v[36:39], v[108:111], v[84:87], v[36:39]
	s_waitcnt lgkmcnt(6)
	v_mfma_f32_16x16x32_bf16 v[40:43], v[112:115], v[84:87], v[40:43]
	s_waitcnt lgkmcnt(5)
	v_mfma_f32_16x16x32_bf16 v[44:47], v[116:119], v[84:87], v[44:47]
	s_waitcnt lgkmcnt(4)
	v_mfma_f32_16x16x32_bf16 v[48:51], v[120:123], v[84:87], v[48:51]
	s_waitcnt lgkmcnt(3)
	v_mfma_f32_16x16x32_bf16 v[52:55], v[124:127], v[84:87], v[52:55]
	s_waitcnt lgkmcnt(2)
	v_mfma_f32_16x16x32_bf16 v[56:59], v[128:131], v[84:87], v[56:59]
	s_waitcnt lgkmcnt(1)
	v_mfma_f32_16x16x32_bf16 v[60:63], v[132:135], v[84:87], v[60:63]
	s_waitcnt lgkmcnt(0)
	v_mfma_f32_16x16x32_bf16 v[64:67], v[136:139], v[84:87], v[64:67]
	s_mov_b32 exec_hi, 0
	global_store_dword v208, v196, s[12:13]
	global_store_dword v208, v197, s[12:13] offset:2048
	global_store_dword v209, v198, s[12:13]
	global_store_dword v209, v199, s[12:13] offset:2048
	s_mov_b64 exec, -1
	s_add_u32 s12, s12, 0x80000
	s_addc_u32 s13, s13, 0
	s_nop 7
	v_cndmask_b32_e64 v145, v36, v37, s[42:43]
	v_cndmask_b32_e64 v147, v38, v39, s[42:43]
	s_nop 1
	v_mov_b32_dpp v146, v145 quad_perm:[1,0,3,2] row_mask:0xf bank_mask:0xf
	v_mov_b32_dpp v156, v147 quad_perm:[1,0,3,2] row_mask:0xf bank_mask:0xf
	v_cndmask_b32_e64 v37, v37, v146, s[42:43]
	v_cndmask_b32_e64 v36, v146, v36, s[42:43]
	v_cndmask_b32_e64 v39, v39, v156, s[42:43]
	v_cndmask_b32_e64 v38, v156, v38, s[42:43]
	v_cndmask_b32_e64 v145, v36, v38, s[44:45]
	v_cndmask_b32_e64 v147, v37, v39, s[44:45]
	s_nop 1
	v_mov_b32_dpp v146, v145 quad_perm:[2,3,0,1] row_mask:0xf bank_mask:0xf
	v_mov_b32_dpp v156, v147 quad_perm:[2,3,0,1] row_mask:0xf bank_mask:0xf
	v_cndmask_b32_e64 v38, v38, v146, s[44:45]
	v_cndmask_b32_e64 v36, v146, v36, s[44:45]
	v_cndmask_b32_e64 v39, v39, v156, s[44:45]
	v_cndmask_b32_e64 v37, v156, v37, s[44:45]
	v_cndmask_b32_e64 v145, v40, v41, s[42:43]
	v_cndmask_b32_e64 v147, v42, v43, s[42:43]
	s_nop 1
	v_mov_b32_dpp v146, v145 quad_perm:[1,0,3,2] row_mask:0xf bank_mask:0xf
	v_mov_b32_dpp v156, v147 quad_perm:[1,0,3,2] row_mask:0xf bank_mask:0xf
	v_cndmask_b32_e64 v41, v41, v146, s[42:43]
	v_cndmask_b32_e64 v40, v146, v40, s[42:43]
	v_cndmask_b32_e64 v43, v43, v156, s[42:43]
	v_cndmask_b32_e64 v42, v156, v42, s[42:43]
	v_cndmask_b32_e64 v145, v40, v42, s[44:45]
	v_cndmask_b32_e64 v147, v41, v43, s[44:45]
	s_nop 1
	v_mov_b32_dpp v146, v145 quad_perm:[2,3,0,1] row_mask:0xf bank_mask:0xf
	v_mov_b32_dpp v156, v147 quad_perm:[2,3,0,1] row_mask:0xf bank_mask:0xf
	v_cndmask_b32_e64 v42, v42, v146, s[44:45]
	v_cndmask_b32_e64 v40, v146, v40, s[44:45]
	v_cndmask_b32_e64 v43, v43, v156, s[44:45]
	v_cndmask_b32_e64 v41, v156, v41, s[44:45]
	v_cndmask_b32_e64 v145, v44, v45, s[42:43]
	v_cndmask_b32_e64 v147, v46, v47, s[42:43]
	s_nop 1
	v_mov_b32_dpp v146, v145 quad_perm:[1,0,3,2] row_mask:0xf bank_mask:0xf
	v_mov_b32_dpp v156, v147 quad_perm:[1,0,3,2] row_mask:0xf bank_mask:0xf
	v_cndmask_b32_e64 v45, v45, v146, s[42:43]
	v_cndmask_b32_e64 v44, v146, v44, s[42:43]
	v_cndmask_b32_e64 v47, v47, v156, s[42:43]
	v_cndmask_b32_e64 v46, v156, v46, s[42:43]
	v_cndmask_b32_e64 v145, v44, v46, s[44:45]
	v_cndmask_b32_e64 v147, v45, v47, s[44:45]
	s_nop 1
	v_mov_b32_dpp v146, v145 quad_perm:[2,3,0,1] row_mask:0xf bank_mask:0xf
	v_mov_b32_dpp v156, v147 quad_perm:[2,3,0,1] row_mask:0xf bank_mask:0xf
; #define LDSBAR() do { asm volatile("s_waitcnt lgkmcnt(0)" ::: "memory"); __builtin_amdgcn_s_barrier(); asm volatile("" ::: "memory"); } while (0)
; __device__ __forceinline__ void hg_seq(const Frame& F, unsigned char* ws, const float* s0, float* sout, float* Og, int seq, bool sample, int vs_base, int nvs) {
;     ...
;     if (active) {
; #pragma unroll
;     for (int kb = 0; kb < 8; ++kb)
; #pragma unroll
;         for (int i = 0; i < 4; ++i) sout[((size_t)seq * 128 + 16 * kb + 4 * q + i) * 128 + 16 * vs + r] = S[kb][i];
;     }
;     LDSBAR();
	v_cndmask_b32_e64 v46, v46, v146, s[44:45]
	v_cndmask_b32_e64 v44, v146, v44, s[44:45]
	v_cndmask_b32_e64 v47, v47, v156, s[44:45]
	v_cndmask_b32_e64 v45, v156, v45, s[44:45]
	v_cndmask_b32_e64 v145, v48, v49, s[42:43]
	v_cndmask_b32_e64 v147, v50, v51, s[42:43]
	s_nop 1
	v_mov_b32_dpp v146, v145 quad_perm:[1,0,3,2] row_mask:0xf bank_mask:0xf
	v_mov_b32_dpp v156, v147 quad_perm:[1,0,3,2] row_mask:0xf bank_mask:0xf
	v_cndmask_b32_e64 v49, v49, v146, s[42:43]
	v_cndmask_b32_e64 v48, v146, v48, s[42:43]
	v_cndmask_b32_e64 v51, v51, v156, s[42:43]
	v_cndmask_b32_e64 v50, v156, v50, s[42:43]
	v_cndmask_b32_e64 v145, v48, v50, s[44:45]
	v_cndmask_b32_e64 v147, v49, v51, s[44:45]
	s_nop 1
	v_mov_b32_dpp v146, v145 quad_perm:[2,3,0,1] row_mask:0xf bank_mask:0xf
	v_mov_b32_dpp v156, v147 quad_perm:[2,3,0,1] row_mask:0xf bank_mask:0xf
	v_cndmask_b32_e64 v50, v50, v146, s[44:45]
	v_cndmask_b32_e64 v48, v146, v48, s[44:45]
	v_cndmask_b32_e64 v51, v51, v156, s[44:45]
	v_cndmask_b32_e64 v49, v156, v49, s[44:45]
	v_cndmask_b32_e64 v145, v52, v53, s[42:43]
	v_cndmask_b32_e64 v147, v54, v55, s[42:43]
	s_nop 1
	v_mov_b32_dpp v146, v145 quad_perm:[1,0,3,2] row_mask:0xf bank_mask:0xf
	v_mov_b32_dpp v156, v147 quad_perm:[1,0,3,2] row_mask:0xf bank_mask:0xf
	v_cndmask_b32_e64 v53, v53, v146, s[42:43]
	v_cndmask_b32_e64 v52, v146, v52, s[42:43]
	v_cndmask_b32_e64 v55, v55, v156, s[42:43]
	v_cndmask_b32_e64 v54, v156, v54, s[42:43]
	v_cndmask_b32_e64 v145, v52, v54, s[44:45]
	v_cndmask_b32_e64 v147, v53, v55, s[44:45]
	s_nop 1
	v_mov_b32_dpp v146, v145 quad_perm:[2,3,0,1] row_mask:0xf bank_mask:0xf
	v_mov_b32_dpp v156, v147 quad_perm:[2,3,0,1] row_mask:0xf bank_mask:0xf
	v_cndmask_b32_e64 v54, v54, v146, s[44:45]
	v_cndmask_b32_e64 v52, v146, v52, s[44:45]
	v_cndmask_b32_e64 v55, v55, v156, s[44:45]
	v_cndmask_b32_e64 v53, v156, v53, s[44:45]
	v_cndmask_b32_e64 v145, v56, v57, s[42:43]
	v_cndmask_b32_e64 v147, v58, v59, s[42:43]
	s_nop 1
	v_mov_b32_dpp v146, v145 quad_perm:[1,0,3,2] row_mask:0xf bank_mask:0xf
	v_mov_b32_dpp v156, v147 quad_perm:[1,0,3,2] row_mask:0xf bank_mask:0xf
	v_cndmask_b32_e64 v57, v57, v146, s[42:43]
	v_cndmask_b32_e64 v56, v146, v56, s[42:43]
	v_cndmask_b32_e64 v59, v59, v156, s[42:43]
	v_cndmask_b32_e64 v58, v156, v58, s[42:43]
	v_cndmask_b32_e64 v145, v56, v58, s[44:45]
	v_cndmask_b32_e64 v147, v57, v59, s[44:45]
	s_nop 1
	v_mov_b32_dpp v146, v145 quad_perm:[2,3,0,1] row_mask:0xf bank_mask:0xf
	v_mov_b32_dpp v156, v147 quad_perm:[2,3,0,1] row_mask:0xf bank_mask:0xf
	v_cndmask_b32_e64 v58, v58, v146, s[44:45]
	v_cndmask_b32_e64 v56, v146, v56, s[44:45]
	v_cndmask_b32_e64 v59, v59, v156, s[44:45]
	v_cndmask_b32_e64 v57, v156, v57, s[44:45]
	v_cndmask_b32_e64 v145, v60, v61, s[42:43]
	v_cndmask_b32_e64 v147, v62, v63, s[42:43]
	s_nop 1
	v_mov_b32_dpp v146, v145 quad_perm:[1,0,3,2] row_mask:0xf bank_mask:0xf
	v_mov_b32_dpp v156, v147 quad_perm:[1,0,3,2] row_mask:0xf bank_mask:0xf
	v_cndmask_b32_e64 v61, v61, v146, s[42:43]
	v_cndmask_b32_e64 v60, v146, v60, s[42:43]
	v_cndmask_b32_e64 v63, v63, v156, s[42:43]
	v_cndmask_b32_e64 v62, v156, v62, s[42:43]
	v_cndmask_b32_e64 v145, v60, v62, s[44:45]
	v_cndmask_b32_e64 v147, v61, v63, s[44:45]
	s_nop 1
	v_mov_b32_dpp v146, v145 quad_perm:[2,3,0,1] row_mask:0xf bank_mask:0xf
	v_mov_b32_dpp v156, v147 quad_perm:[2,3,0,1] row_mask:0xf bank_mask:0xf
	v_cndmask_b32_e64 v62, v62, v146, s[44:45]
	v_cndmask_b32_e64 v60, v146, v60, s[44:45]
	v_cndmask_b32_e64 v63, v63, v156, s[44:45]
	v_cndmask_b32_e64 v61, v156, v61, s[44:45]
	v_cndmask_b32_e64 v145, v64, v65, s[42:43]
	v_cndmask_b32_e64 v147, v66, v67, s[42:43]
	s_nop 1
	v_mov_b32_dpp v146, v145 quad_perm:[1,0,3,2] row_mask:0xf bank_mask:0xf
	v_mov_b32_dpp v156, v147 quad_perm:[1,0,3,2] row_mask:0xf bank_mask:0xf
	v_cndmask_b32_e64 v65, v65, v146, s[42:43]
	v_cndmask_b32_e64 v64, v146, v64, s[42:43]
	v_cndmask_b32_e64 v67, v67, v156, s[42:43]
	v_cndmask_b32_e64 v66, v156, v66, s[42:43]
	v_cndmask_b32_e64 v145, v64, v66, s[44:45]
	v_cndmask_b32_e64 v147, v65, v67, s[44:45]
	s_nop 1
	v_mov_b32_dpp v146, v145 quad_perm:[2,3,0,1] row_mask:0xf bank_mask:0xf
	v_mov_b32_dpp v156, v147 quad_perm:[2,3,0,1] row_mask:0xf bank_mask:0xf
	v_cndmask_b32_e64 v66, v66, v146, s[44:45]
	v_cndmask_b32_e64 v64, v146, v64, s[44:45]
	v_cndmask_b32_e64 v67, v67, v156, s[44:45]
	v_cndmask_b32_e64 v65, v156, v65, s[44:45]
	global_store_dwordx4 v200, v[36:39], s[10:11]
	global_store_dwordx4 v201, v[40:43], s[10:11]
	global_store_dwordx4 v202, v[44:47], s[10:11]
	global_store_dwordx4 v203, v[48:51], s[10:11]
	global_store_dwordx4 v204, v[52:55], s[10:11]
	global_store_dwordx4 v205, v[56:59], s[10:11]
	global_store_dwordx4 v206, v[60:63], s[10:11]
	global_store_dwordx4 v207, v[64:67], s[10:11]
	s_add_u32 s10, s10, s34
	s_addc_u32 s11, s11, 0
	s_waitcnt lgkmcnt(0)
	s_barrier
